# v99 + sc1 policy on the P0 XN bf16/fp8 row stores only (weight-tile stores left plain)
# baseline (speedup 1.0000x reference)
; #define GAS __attribute__((address_space(1)))
; __host__ __device__ __forceinline__ size_t tl_off(int row, int k, int K) { return ((((size_t)(row >> 4) * (size_t)(K >> 5)) + (size_t)(k >> 5)) << 9) + (size_t)((row & 15) * 32 + (k & 31)); }
; __device__ __forceinline__ unsigned pk2(float lo, float hi) { return f2bf(lo) | (f2bf(hi) << 16); }
; __device__ __forceinline__ void p0_prologue(Frame& F) {
;     ...
;             const bool lodd = lane & 1, lhi = lane & 2;
;             f32x4 gg[4];
;             { int l_ = lane; asm volatile("" : "+v"(l_));
; #pragma unroll
;               for (int j = 0; j < 4; ++j) gg[j] = *((const f32x4*)F.g1 + l_ + 64 * j); }
; #pragma unroll
;             for (int rq = 0; rq < 2; ++rq) {
;                 unsigned q8[4][4];
; #pragma unroll
;                 for (int rh = 0; rh < 2; ++rh) {
;                     const int r0 = 4 * rq + 2 * rh, r1 = r0 + 1;
; #pragma unroll
;                     for (int j = 0; j < 4; ++j) {
;                         const float x0 = v[r0][j].x * rs8[r0] * gg[j].x, x1 = v[r0][j].y * rs8[r0] * gg[j].y, x2 = v[r0][j].z * rs8[r0] * gg[j].z, x3 = v[r0][j].w * rs8[r0] * gg[j].w;
;                         const float y0 = v[r1][j].x * rs8[r1] * gg[j].x, y1 = v[r1][j].y * rs8[r1] * gg[j].y, y2 = v[r1][j].z * rs8[r1] * gg[j].z, y3 = v[r1][j].w * rs8[r1] * gg[j].w;
;                         const unsigned a0 = pk2(x0, x1), a1 = pk2(x2, x3), b0 = pk2(y0, y1), b1 = pk2(y2, y3);
;                         q8[2 * rh][j] = pk4_fp8(x0, x1, x2, x3); q8[2 * rh + 1][j] = pk4_fp8(y0, y1, y2, y3);
;                         const unsigned t0 = lodd ? a0 : b0, t1 = lodd ? a1 : b1;
;                         const unsigned g0 = (unsigned)__builtin_amdgcn_mov_dpp((int)t0, 0xB1, 0xf, 0xf, true), g1 = (unsigned)__builtin_amdgcn_mov_dpp((int)t1, 0xB1, 0xf, 0xf, true);
;                         u32x4 o; o.x = lodd ? g0 : a0; o.y = lodd ? g1 : a1; o.z = lodd ? b0 : g0; o.w = lodd ? b1 : g1;
;                         *(GAS u32x4*)(F.XN + tl_off(m0 + r0 + (lane & 1), 8 * (lane >> 1) + 256 * j, D)) = o;
;                         __builtin_amdgcn_sched_barrier(0);
;                     }
.LBB0_28:
	s_or_b64 exec, exec, s[8:9]
	v_mov_b32_e32 v128, v144
	v_add_u32_e32 v228, s70, v217
	v_ashrrev_i32_e32 v129, 31, v128
	v_lshl_add_u64 v[128:129], v[128:129], 4, s[38:39]
	global_load_dwordx4 v[140:143], v[128:129], off
	global_load_dwordx4 v[136:139], v[128:129], off offset:1024
	global_load_dwordx4 v[132:135], v[128:129], off offset:2048
	s_nop 0
	global_load_dwordx4 v[128:131], v[128:129], off offset:3072
	v_ashrrev_i32_e32 v236, 4, v228
	v_mov_b32_e32 v208, v16
	v_mov_b32_e32 v209, v18
	v_ashrrev_i32_e32 v237, 31, v236
	v_mov_b32_e32 v218, v17
	v_mov_b32_e32 v219, v19
	v_mov_b32_e32 v232, v48
	v_mov_b32_e32 v233, v50
	v_mov_b32_e32 v234, v49
	v_mov_b32_e32 v235, v51
	v_pk_mul_f32 v[238:239], v[208:209], v[214:215] op_sel_hi:[1,0]
	v_lshlrev_b64 v[208:209], 15, v[236:237]
	v_pk_mul_f32 v[240:241], v[218:219], v[214:215] op_sel_hi:[1,0]
	v_pk_mul_f32 v[232:233], v[232:233], v[216:217] op_sel_hi:[1,0]
	v_pk_mul_f32 v[234:235], v[234:235], v[216:217] op_sel_hi:[1,0]
	v_lshl_add_u64 v[218:219], s[62:63], 0, v[208:209]
	v_mov_b32_e32 v229, 0
	v_mov_b32_e32 v230, 0
	v_lshlrev_b32_e32 v152, 5, v228
	v_and_or_b32 v152, v152, s54, v220
	v_lshlrev_b32_e32 v152, 1, v152
	v_lshl_add_u64 v[236:237], v[218:219], 0, v[148:149]
	v_add_u32_e32 v227, s70, v221
	s_waitcnt vmcnt(3)
	v_mov_b32_e32 v208, v140
	v_mov_b32_e32 v209, v142
	v_mov_b32_e32 v142, v141
	v_pk_mul_f32 v[140:141], v[238:239], v[208:209]
	v_pk_mul_f32 v[238:239], v[240:241], v[142:143]
	v_pk_mul_f32 v[232:233], v[232:233], v[208:209]
	v_pk_mul_f32 v[234:235], v[234:235], v[142:143]
	v_and_b32_sdwa v240, v140, v226 dst_sel:DWORD dst_unused:UNUSED_PAD src0_sel:WORD_1 src1_sel:DWORD
	v_and_b32_sdwa v241, v239, v226 dst_sel:DWORD dst_unused:UNUSED_PAD src0_sel:WORD_1 src1_sel:DWORD
	v_and_b32_sdwa v242, v238, v226 dst_sel:DWORD dst_unused:UNUSED_PAD src0_sel:WORD_1 src1_sel:DWORD
	v_cvt_pk_fp8_f32 v229, v140, v238
	v_and_b32_sdwa v245, v235, v226 dst_sel:DWORD dst_unused:UNUSED_PAD src0_sel:WORD_1 src1_sel:DWORD
	v_and_b32_sdwa v246, v234, v226 dst_sel:DWORD dst_unused:UNUSED_PAD src0_sel:WORD_1 src1_sel:DWORD
	v_cvt_pk_fp8_f32 v230, v232, v234
	v_and_b32_sdwa v231, v141, v226 dst_sel:DWORD dst_unused:UNUSED_PAD src0_sel:WORD_1 src1_sel:DWORD
	v_and_b32_sdwa v243, v233, v226 dst_sel:DWORD dst_unused:UNUSED_PAD src0_sel:WORD_1 src1_sel:DWORD
	v_and_b32_sdwa v244, v232, v226 dst_sel:DWORD dst_unused:UNUSED_PAD src0_sel:WORD_1 src1_sel:DWORD
	v_add3_u32 v140, v140, v240, s96
	v_add3_u32 v240, v239, v241, s96
	v_add3_u32 v238, v238, v242, s96
	v_add3_u32 v242, v235, v245, s96
	v_add3_u32 v234, v234, v246, s96
	v_add3_u32 v231, v141, v231, s96
	v_add3_u32 v232, v232, v244, s96
	v_add3_u32 v241, v233, v243, s96
	v_and_b32_e32 v240, 0xffff0000, v240
	v_and_b32_e32 v238, 0xffff0000, v238
	v_and_b32_e32 v242, 0xffff0000, v242
	v_and_b32_e32 v234, 0xffff0000, v234
	v_or_b32_sdwa v231, v240, v231 dst_sel:DWORD dst_unused:UNUSED_PAD src0_sel:DWORD src1_sel:WORD_1
	v_or_b32_sdwa v140, v238, v140 dst_sel:DWORD dst_unused:UNUSED_PAD src0_sel:DWORD src1_sel:WORD_1
	v_or_b32_sdwa v238, v242, v241 dst_sel:DWORD dst_unused:UNUSED_PAD src0_sel:DWORD src1_sel:WORD_1
	v_or_b32_sdwa v232, v234, v232 dst_sel:DWORD dst_unused:UNUSED_PAD src0_sel:DWORD src1_sel:WORD_1
	v_cvt_pk_fp8_f32 v229, v141, v239 op_sel:[0,0,1]
	v_cvt_pk_fp8_f32 v230, v233, v235 op_sel:[0,0,1]
	v_cndmask_b32_e64 v141, v140, v232, s[4:5]
	v_cndmask_b32_e64 v233, v231, v238, s[4:5]
	s_nop 0
	v_mov_b32_dpp v141, v141 quad_perm:[1,0,3,2] row_mask:0xf bank_mask:0xf bound_ctrl:1
	v_mov_b32_dpp v233, v233 quad_perm:[1,0,3,2] row_mask:0xf bank_mask:0xf bound_ctrl:1
	v_cndmask_b32_e64 v235, v238, v233, s[4:5]
	v_cndmask_b32_e64 v234, v232, v141, s[4:5]
	v_cndmask_b32_e64 v233, v233, v231, s[4:5]
	v_cndmask_b32_e64 v232, v141, v140, s[4:5]
	v_lshl_add_u64 v[140:141], v[236:237], 0, v[152:153]
	global_store_dwordx4 v[140:141], v[232:235], off sc1
	v_mov_b32_e32 v140, v12
	v_mov_b32_e32 v141, v14
	v_pk_mul_f32 v[232:233], v[140:141], v[214:215] op_sel_hi:[1,0]
	v_mov_b32_e32 v140, v13
	v_mov_b32_e32 v141, v15
	v_pk_mul_f32 v[234:235], v[140:141], v[214:215] op_sel_hi:[1,0]
	v_mov_b32_e32 v140, v36
	v_mov_b32_e32 v141, v38
	v_pk_mul_f32 v[236:237], v[140:141], v[216:217] op_sel_hi:[1,0]
	v_mov_b32_e32 v140, v37
	v_mov_b32_e32 v141, v39
	v_pk_mul_f32 v[238:239], v[140:141], v[216:217] op_sel_hi:[1,0]
	s_waitcnt vmcnt(3)
; #define GAS __attribute__((address_space(1)))
; __host__ __device__ __forceinline__ size_t tl_off(int row, int k, int K) { return ((((size_t)(row >> 4) * (size_t)(K >> 5)) + (size_t)(k >> 5)) << 9) + (size_t)((row & 15) * 32 + (k & 31)); }
; __device__ __forceinline__ unsigned pk2(float lo, float hi) { return f2bf(lo) | (f2bf(hi) << 16); }
; __device__ __forceinline__ void p0_prologue(Frame& F) {
;     ...
;                 for (int rh = 0; rh < 2; ++rh) {
;                     const int r0 = 4 * rq + 2 * rh, r1 = r0 + 1;
; #pragma unroll
;                     for (int j = 0; j < 4; ++j) {
;                         const float x0 = v[r0][j].x * rs8[r0] * gg[j].x, x1 = v[r0][j].y * rs8[r0] * gg[j].y, x2 = v[r0][j].z * rs8[r0] * gg[j].z, x3 = v[r0][j].w * rs8[r0] * gg[j].w;
;                         const float y0 = v[r1][j].x * rs8[r1] * gg[j].x, y1 = v[r1][j].y * rs8[r1] * gg[j].y, y2 = v[r1][j].z * rs8[r1] * gg[j].z, y3 = v[r1][j].w * rs8[r1] * gg[j].w;
;                         const unsigned a0 = pk2(x0, x1), a1 = pk2(x2, x3), b0 = pk2(y0, y1), b1 = pk2(y2, y3);
;                         q8[2 * rh][j] = pk4_fp8(x0, x1, x2, x3); q8[2 * rh + 1][j] = pk4_fp8(y0, y1, y2, y3);
;                         const unsigned t0 = lodd ? a0 : b0, t1 = lodd ? a1 : b1;
;                         const unsigned g0 = (unsigned)__builtin_amdgcn_mov_dpp((int)t0, 0xB1, 0xf, 0xf, true), g1 = (unsigned)__builtin_amdgcn_mov_dpp((int)t1, 0xB1, 0xf, 0xf, true);
;                         u32x4 o; o.x = lodd ? g0 : a0; o.y = lodd ? g1 : a1; o.z = lodd ? b0 : g0; o.w = lodd ? b1 : g1;
;                         *(GAS u32x4*)(F.XN + tl_off(m0 + r0 + (lane & 1), 8 * (lane >> 1) + 256 * j, D)) = o;
;                         __builtin_amdgcn_sched_barrier(0);
;                     }
	v_mov_b32_e32 v140, v136
	v_mov_b32_e32 v141, v138
	v_pk_mul_f32 v[232:233], v[232:233], v[140:141]
	v_mov_b32_e32 v138, v137
	v_pk_mul_f32 v[136:137], v[234:235], v[138:139]
	v_and_b32_sdwa v231, v233, v226 dst_sel:DWORD dst_unused:UNUSED_PAD src0_sel:WORD_1 src1_sel:DWORD
	v_add3_u32 v235, v233, v231, s96
	v_and_b32_sdwa v231, v137, v226 dst_sel:DWORD dst_unused:UNUSED_PAD src0_sel:WORD_1 src1_sel:DWORD
	v_add3_u32 v231, v137, v231, s96
	v_and_b32_e32 v241, 0xffff0000, v231
	v_mov_b32_e32 v231, v153
	v_cvt_pk_fp8_f32 v231, v232, v136
	v_and_b32_sdwa v240, v136, v226 dst_sel:DWORD dst_unused:UNUSED_PAD src0_sel:WORD_1 src1_sel:DWORD
	v_and_b32_sdwa v234, v232, v226 dst_sel:DWORD dst_unused:UNUSED_PAD src0_sel:WORD_1 src1_sel:DWORD
	v_add3_u32 v240, v136, v240, s96
	v_add3_u32 v234, v232, v234, s96
	v_and_b32_e32 v136, 0xffff0000, v240
	v_or_b32_sdwa v240, v241, v235 dst_sel:DWORD dst_unused:UNUSED_PAD src0_sel:DWORD src1_sel:WORD_1
	v_or_b32_sdwa v241, v136, v234 dst_sel:DWORD dst_unused:UNUSED_PAD src0_sel:DWORD src1_sel:WORD_1
	v_cvt_pk_fp8_f32 v231, v233, v137 op_sel:[0,0,1]
	v_pk_mul_f32 v[136:137], v[236:237], v[140:141]
	v_pk_mul_f32 v[234:235], v[238:239], v[138:139]
	v_and_b32_sdwa v232, v137, v226 dst_sel:DWORD dst_unused:UNUSED_PAD src0_sel:WORD_1 src1_sel:DWORD
	v_add3_u32 v236, v137, v232, s96
	v_and_b32_sdwa v232, v235, v226 dst_sel:DWORD dst_unused:UNUSED_PAD src0_sel:WORD_1 src1_sel:DWORD
	v_add3_u32 v232, v235, v232, s96
	v_and_b32_e32 v238, 0xffff0000, v232
	v_mov_b32_e32 v232, v153
	v_and_b32_sdwa v237, v234, v226 dst_sel:DWORD dst_unused:UNUSED_PAD src0_sel:WORD_1 src1_sel:DWORD
	v_cvt_pk_fp8_f32 v232, v136, v234
	v_and_b32_sdwa v233, v136, v226 dst_sel:DWORD dst_unused:UNUSED_PAD src0_sel:WORD_1 src1_sel:DWORD
	v_add3_u32 v237, v234, v237, s96
	v_add3_u32 v233, v136, v233, s96
	v_and_b32_e32 v136, 0xffff0000, v237
	v_or_b32_sdwa v234, v238, v236 dst_sel:DWORD dst_unused:UNUSED_PAD src0_sel:DWORD src1_sel:WORD_1
	v_or_b32_sdwa v136, v136, v233 dst_sel:DWORD dst_unused:UNUSED_PAD src0_sel:DWORD src1_sel:WORD_1
	v_cvt_pk_fp8_f32 v232, v137, v235 op_sel:[0,0,1]
	v_cndmask_b32_e64 v137, v241, v136, s[4:5]
	v_cndmask_b32_e64 v233, v240, v234, s[4:5]
	s_nop 0
	v_mov_b32_dpp v137, v137 quad_perm:[1,0,3,2] row_mask:0xf bank_mask:0xf bound_ctrl:1
	v_mov_b32_dpp v233, v233 quad_perm:[1,0,3,2] row_mask:0xf bank_mask:0xf bound_ctrl:1
	v_cndmask_b32_e64 v237, v234, v233, s[4:5]
	v_cndmask_b32_e64 v236, v136, v137, s[4:5]
	v_cndmask_b32_e64 v234, v137, v241, s[4:5]
	v_lshl_add_u64 v[136:137], v[218:219], 0, v[154:155]
	v_cndmask_b32_e64 v235, v233, v240, s[4:5]
	v_lshl_add_u64 v[136:137], v[136:137], 0, v[152:153]
	global_store_dwordx4 v[136:137], v[234:237], off sc1
	v_mov_b32_e32 v136, v8
	v_mov_b32_e32 v137, v10
	v_pk_mul_f32 v[234:235], v[136:137], v[214:215] op_sel_hi:[1,0]
	v_mov_b32_e32 v136, v9
	v_mov_b32_e32 v137, v11
	v_pk_mul_f32 v[236:237], v[136:137], v[214:215] op_sel_hi:[1,0]
	v_mov_b32_e32 v136, v32
	v_mov_b32_e32 v137, v34
	v_pk_mul_f32 v[238:239], v[136:137], v[216:217] op_sel_hi:[1,0]
	v_mov_b32_e32 v136, v33
	v_mov_b32_e32 v137, v35
	v_pk_mul_f32 v[240:241], v[136:137], v[216:217] op_sel_hi:[1,0]
	s_waitcnt vmcnt(3)
	v_mov_b32_e32 v136, v132
	v_mov_b32_e32 v137, v134
	v_mov_b32_e32 v134, v133
	v_pk_mul_f32 v[234:235], v[234:235], v[136:137]
	v_pk_mul_f32 v[132:133], v[236:237], v[134:135]
	v_mov_b32_e32 v243, v153
	v_cvt_pk_fp8_f32 v243, v234, v132
	v_and_b32_sdwa v242, v132, v226 dst_sel:DWORD dst_unused:UNUSED_PAD src0_sel:WORD_1 src1_sel:DWORD
	v_and_b32_sdwa v236, v234, v226 dst_sel:DWORD dst_unused:UNUSED_PAD src0_sel:WORD_1 src1_sel:DWORD
	v_add3_u32 v242, v132, v242, s96
	v_and_b32_sdwa v233, v235, v226 dst_sel:DWORD dst_unused:UNUSED_PAD src0_sel:WORD_1 src1_sel:DWORD
	v_add3_u32 v236, v234, v236, s96
	v_and_b32_sdwa v237, v133, v226 dst_sel:DWORD dst_unused:UNUSED_PAD src0_sel:WORD_1 src1_sel:DWORD
	v_and_b32_e32 v132, 0xffff0000, v242
	v_add3_u32 v233, v235, v233, s96
	v_add3_u32 v237, v133, v237, s96
	v_or_b32_sdwa v242, v132, v236 dst_sel:DWORD dst_unused:UNUSED_PAD src0_sel:DWORD src1_sel:WORD_1
	v_cvt_pk_fp8_f32 v243, v235, v133 op_sel:[0,0,1]
	v_pk_mul_f32 v[132:133], v[238:239], v[136:137]
	v_pk_mul_f32 v[234:235], v[240:241], v[134:135]
	v_mov_b32_e32 v244, v153
	v_and_b32_e32 v237, 0xffff0000, v237
	v_and_b32_sdwa v238, v235, v226 dst_sel:DWORD dst_unused:UNUSED_PAD src0_sel:WORD_1 src1_sel:DWORD
	v_and_b32_sdwa v239, v234, v226 dst_sel:DWORD dst_unused:UNUSED_PAD src0_sel:WORD_1 src1_sel:DWORD
	v_cvt_pk_fp8_f32 v244, v132, v234
	v_or_b32_sdwa v233, v237, v233 dst_sel:DWORD dst_unused:UNUSED_PAD src0_sel:DWORD src1_sel:WORD_1
	v_and_b32_sdwa v236, v133, v226 dst_sel:DWORD dst_unused:UNUSED_PAD src0_sel:WORD_1 src1_sel:DWORD
	v_and_b32_sdwa v237, v132, v226 dst_sel:DWORD dst_unused:UNUSED_PAD src0_sel:WORD_1 src1_sel:DWORD
	v_add3_u32 v238, v235, v238, s96
	v_add3_u32 v239, v234, v239, s96
	v_add3_u32 v237, v132, v237, s96
	v_add3_u32 v236, v133, v236, s96
	v_and_b32_e32 v238, 0xffff0000, v238
	v_and_b32_e32 v132, 0xffff0000, v239
	v_or_b32_sdwa v234, v238, v236 dst_sel:DWORD dst_unused:UNUSED_PAD src0_sel:DWORD src1_sel:WORD_1
	v_or_b32_sdwa v132, v132, v237 dst_sel:DWORD dst_unused:UNUSED_PAD src0_sel:DWORD src1_sel:WORD_1
	v_cvt_pk_fp8_f32 v244, v133, v235 op_sel:[0,0,1]
	v_cndmask_b32_e64 v133, v242, v132, s[4:5]
	v_cndmask_b32_e64 v235, v233, v234, s[4:5]
	s_nop 0
	v_mov_b32_dpp v133, v133 quad_perm:[1,0,3,2] row_mask:0xf bank_mask:0xf bound_ctrl:1
	v_mov_b32_dpp v235, v235 quad_perm:[1,0,3,2] row_mask:0xf bank_mask:0xf bound_ctrl:1
	v_cndmask_b32_e64 v237, v234, v235, s[4:5]
	v_cndmask_b32_e64 v236, v132, v133, s[4:5]
	v_cndmask_b32_e64 v234, v133, v242, s[4:5]
	v_lshl_add_u64 v[132:133], v[218:219], 0, v[156:157]
	v_cndmask_b32_e64 v235, v235, v233, s[4:5]
	v_lshl_add_u64 v[132:133], v[132:133], 0, v[152:153]
	global_store_dwordx4 v[132:133], v[234:237], off sc1
	v_mov_b32_e32 v132, v4
	v_mov_b32_e32 v133, v6
	v_pk_mul_f32 v[234:235], v[132:133], v[214:215] op_sel_hi:[1,0]
	v_mov_b32_e32 v132, v5
	v_mov_b32_e32 v133, v7
	v_pk_mul_f32 v[236:237], v[132:133], v[214:215] op_sel_hi:[1,0]
	v_mov_b32_e32 v132, v44
	v_mov_b32_e32 v133, v46
	v_pk_mul_f32 v[238:239], v[132:133], v[216:217] op_sel_hi:[1,0]
	v_mov_b32_e32 v132, v45
	v_mov_b32_e32 v133, v47
	v_pk_mul_f32 v[240:241], v[132:133], v[216:217] op_sel_hi:[1,0]
	s_waitcnt vmcnt(3)
; #define GAS __attribute__((address_space(1)))
; __host__ __device__ __forceinline__ size_t tl_off(int row, int k, int K) { return ((((size_t)(row >> 4) * (size_t)(K >> 5)) + (size_t)(k >> 5)) << 9) + (size_t)((row & 15) * 32 + (k & 31)); }
; __device__ __forceinline__ unsigned pk2(float lo, float hi) { return f2bf(lo) | (f2bf(hi) << 16); }
; __device__ __forceinline__ void p0_prologue(Frame& F) {
;     ...
;                 for (int rh = 0; rh < 2; ++rh) {
;                     const int r0 = 4 * rq + 2 * rh, r1 = r0 + 1;
; #pragma unroll
;                     for (int j = 0; j < 4; ++j) {
;                         const float x0 = v[r0][j].x * rs8[r0] * gg[j].x, x1 = v[r0][j].y * rs8[r0] * gg[j].y, x2 = v[r0][j].z * rs8[r0] * gg[j].z, x3 = v[r0][j].w * rs8[r0] * gg[j].w;
;                         const float y0 = v[r1][j].x * rs8[r1] * gg[j].x, y1 = v[r1][j].y * rs8[r1] * gg[j].y, y2 = v[r1][j].z * rs8[r1] * gg[j].z, y3 = v[r1][j].w * rs8[r1] * gg[j].w;
;                         const unsigned a0 = pk2(x0, x1), a1 = pk2(x2, x3), b0 = pk2(y0, y1), b1 = pk2(y2, y3);
;                         q8[2 * rh][j] = pk4_fp8(x0, x1, x2, x3); q8[2 * rh + 1][j] = pk4_fp8(y0, y1, y2, y3);
;                         const unsigned t0 = lodd ? a0 : b0, t1 = lodd ? a1 : b1;
;                         const unsigned g0 = (unsigned)__builtin_amdgcn_mov_dpp((int)t0, 0xB1, 0xf, 0xf, true), g1 = (unsigned)__builtin_amdgcn_mov_dpp((int)t1, 0xB1, 0xf, 0xf, true);
;                         u32x4 o; o.x = lodd ? g0 : a0; o.y = lodd ? g1 : a1; o.z = lodd ? b0 : g0; o.w = lodd ? b1 : g1;
;                         *(GAS u32x4*)(F.XN + tl_off(m0 + r0 + (lane & 1), 8 * (lane >> 1) + 256 * j, D)) = o;
;                         __builtin_amdgcn_sched_barrier(0);
;                     }
	v_mov_b32_e32 v132, v128
	v_mov_b32_e32 v133, v130
	v_mov_b32_e32 v130, v129
	v_pk_mul_f32 v[234:235], v[234:235], v[132:133]
	v_pk_mul_f32 v[128:129], v[236:237], v[130:131]
	v_mov_b32_e32 v242, v153
	v_cvt_pk_fp8_f32 v242, v234, v128
	v_and_b32_sdwa v236, v128, v226 dst_sel:DWORD dst_unused:UNUSED_PAD src0_sel:WORD_1 src1_sel:DWORD
	v_and_b32_sdwa v216, v234, v226 dst_sel:DWORD dst_unused:UNUSED_PAD src0_sel:WORD_1 src1_sel:DWORD
	v_add3_u32 v236, v128, v236, s96
	v_and_b32_sdwa v214, v235, v226 dst_sel:DWORD dst_unused:UNUSED_PAD src0_sel:WORD_1 src1_sel:DWORD
	v_add3_u32 v216, v234, v216, s96
	v_and_b32_sdwa v233, v129, v226 dst_sel:DWORD dst_unused:UNUSED_PAD src0_sel:WORD_1 src1_sel:DWORD
	v_and_b32_e32 v128, 0xffff0000, v236
	v_add3_u32 v214, v235, v214, s96
	v_add3_u32 v233, v129, v233, s96
	v_or_b32_sdwa v216, v128, v216 dst_sel:DWORD dst_unused:UNUSED_PAD src0_sel:DWORD src1_sel:WORD_1
	v_cvt_pk_fp8_f32 v242, v235, v129 op_sel:[0,0,1]
	v_pk_mul_f32 v[128:129], v[238:239], v[132:133]
	v_pk_mul_f32 v[234:235], v[240:241], v[130:131]
	v_mov_b32_e32 v240, v153
	v_and_b32_e32 v233, 0xffff0000, v233
	v_and_b32_sdwa v237, v235, v226 dst_sel:DWORD dst_unused:UNUSED_PAD src0_sel:WORD_1 src1_sel:DWORD
	v_and_b32_sdwa v238, v234, v226 dst_sel:DWORD dst_unused:UNUSED_PAD src0_sel:WORD_1 src1_sel:DWORD
	v_cvt_pk_fp8_f32 v240, v128, v234
	v_or_b32_sdwa v214, v233, v214 dst_sel:DWORD dst_unused:UNUSED_PAD src0_sel:DWORD src1_sel:WORD_1
	v_and_b32_sdwa v233, v129, v226 dst_sel:DWORD dst_unused:UNUSED_PAD src0_sel:WORD_1 src1_sel:DWORD
	v_and_b32_sdwa v236, v128, v226 dst_sel:DWORD dst_unused:UNUSED_PAD src0_sel:WORD_1 src1_sel:DWORD
	v_add3_u32 v237, v235, v237, s96
	v_add3_u32 v238, v234, v238, s96
	v_add3_u32 v236, v128, v236, s96
	v_add3_u32 v233, v129, v233, s96
	v_and_b32_e32 v237, 0xffff0000, v237
	v_and_b32_e32 v128, 0xffff0000, v238
	v_or_b32_sdwa v233, v237, v233 dst_sel:DWORD dst_unused:UNUSED_PAD src0_sel:DWORD src1_sel:WORD_1
	v_or_b32_sdwa v128, v128, v236 dst_sel:DWORD dst_unused:UNUSED_PAD src0_sel:DWORD src1_sel:WORD_1
	v_cvt_pk_fp8_f32 v240, v129, v235 op_sel:[0,0,1]
	v_cndmask_b32_e64 v129, v216, v128, s[4:5]
	v_cndmask_b32_e64 v234, v214, v233, s[4:5]
	s_nop 0
	v_mov_b32_dpp v129, v129 quad_perm:[1,0,3,2] row_mask:0xf bank_mask:0xf bound_ctrl:1
	v_mov_b32_dpp v234, v234 quad_perm:[1,0,3,2] row_mask:0xf bank_mask:0xf bound_ctrl:1
	v_cndmask_b32_e64 v237, v233, v234, s[4:5]
	v_cndmask_b32_e64 v236, v128, v129, s[4:5]
	v_cndmask_b32_e64 v235, v234, v214, s[4:5]
	v_cndmask_b32_e64 v234, v129, v216, s[4:5]
	v_lshl_add_u64 v[128:129], v[218:219], 0, v[158:159]
	v_lshl_add_u64 v[128:129], v[128:129], 0, v[152:153]
	global_store_dwordx4 v[128:129], v[234:237], off sc1
	v_mov_b32_e32 v218, v80
	v_mov_b32_e32 v219, v82
	v_mov_b32_e32 v234, v81
	v_mov_b32_e32 v235, v83
	v_pk_mul_f32 v[218:219], v[218:219], v[210:211] op_sel_hi:[1,0]
	v_pk_mul_f32 v[234:235], v[234:235], v[210:211] op_sel_hi:[1,0]
	v_pk_mul_f32 v[218:219], v[218:219], v[208:209]
	v_pk_mul_f32 v[234:235], v[234:235], v[142:143]
	v_mov_b32_e32 v245, v153
	v_cvt_pk_fp8_f32 v245, v218, v234
	v_and_b32_sdwa v241, v234, v226 dst_sel:DWORD dst_unused:UNUSED_PAD src0_sel:WORD_1 src1_sel:DWORD
	v_mov_b32_e32 v236, v112
	v_mov_b32_e32 v237, v114
	v_mov_b32_e32 v238, v113
	v_mov_b32_e32 v239, v115
	v_and_b32_sdwa v216, v218, v226 dst_sel:DWORD dst_unused:UNUSED_PAD src0_sel:WORD_1 src1_sel:DWORD
	v_add3_u32 v241, v234, v241, s96
	v_pk_mul_f32 v[236:237], v[236:237], v[212:213] op_sel_hi:[1,0]
	v_pk_mul_f32 v[238:239], v[238:239], v[212:213] op_sel_hi:[1,0]
	v_and_b32_sdwa v214, v219, v226 dst_sel:DWORD dst_unused:UNUSED_PAD src0_sel:WORD_1 src1_sel:DWORD
	v_add3_u32 v216, v218, v216, s96
	v_and_b32_sdwa v233, v235, v226 dst_sel:DWORD dst_unused:UNUSED_PAD src0_sel:WORD_1 src1_sel:DWORD
	v_and_b32_e32 v218, 0xffff0000, v241
	v_add3_u32 v214, v219, v214, s96
	v_add3_u32 v233, v235, v233, s96
	v_or_b32_sdwa v216, v218, v216 dst_sel:DWORD dst_unused:UNUSED_PAD src0_sel:DWORD src1_sel:WORD_1
	v_cvt_pk_fp8_f32 v245, v219, v235 op_sel:[0,0,1]
	v_pk_mul_f32 v[218:219], v[236:237], v[208:209]
	v_pk_mul_f32 v[234:235], v[238:239], v[142:143]
	v_mov_b32_e32 v241, v153
	v_and_b32_e32 v233, 0xffff0000, v233
	v_and_b32_sdwa v237, v235, v226 dst_sel:DWORD dst_unused:UNUSED_PAD src0_sel:WORD_1 src1_sel:DWORD
	v_and_b32_sdwa v238, v234, v226 dst_sel:DWORD dst_unused:UNUSED_PAD src0_sel:WORD_1 src1_sel:DWORD
	v_cvt_pk_fp8_f32 v241, v218, v234
	v_add_u32_e32 v152, 2, v228
	v_or_b32_sdwa v214, v233, v214 dst_sel:DWORD dst_unused:UNUSED_PAD src0_sel:DWORD src1_sel:WORD_1
	v_and_b32_sdwa v233, v219, v226 dst_sel:DWORD dst_unused:UNUSED_PAD src0_sel:WORD_1 src1_sel:DWORD
	v_and_b32_sdwa v236, v218, v226 dst_sel:DWORD dst_unused:UNUSED_PAD src0_sel:WORD_1 src1_sel:DWORD
	v_add3_u32 v237, v235, v237, s96
	v_add3_u32 v238, v234, v238, s96
	v_ashrrev_i32_e32 v128, 4, v152
	v_add3_u32 v236, v218, v236, s96
	v_add3_u32 v233, v219, v233, s96
	v_and_b32_e32 v237, 0xffff0000, v237
	v_and_b32_e32 v218, 0xffff0000, v238
	v_ashrrev_i32_e32 v129, 31, v128
	v_or_b32_sdwa v233, v237, v233 dst_sel:DWORD dst_unused:UNUSED_PAD src0_sel:DWORD src1_sel:WORD_1
	v_or_b32_sdwa v218, v218, v236 dst_sel:DWORD dst_unused:UNUSED_PAD src0_sel:DWORD src1_sel:WORD_1
	v_lshlrev_b32_e32 v152, 5, v152
	v_lshlrev_b64 v[128:129], 15, v[128:129]
	v_cvt_pk_fp8_f32 v241, v219, v235 op_sel:[0,0,1]
	v_cndmask_b32_e64 v219, v216, v218, s[4:5]
	v_cndmask_b32_e64 v234, v214, v233, s[4:5]
	v_and_or_b32 v152, v152, s54, v220
	v_mov_b32_dpp v219, v219 quad_perm:[1,0,3,2] row_mask:0xf bank_mask:0xf bound_ctrl:1
; #define GAS __attribute__((address_space(1)))
; __host__ __device__ __forceinline__ size_t tl_off(int row, int k, int K) { return ((((size_t)(row >> 4) * (size_t)(K >> 5)) + (size_t)(k >> 5)) << 9) + (size_t)((row & 15) * 32 + (k & 31)); }
; __device__ __forceinline__ unsigned pk2(float lo, float hi) { return f2bf(lo) | (f2bf(hi) << 16); }
; __device__ __forceinline__ void p0_prologue(Frame& F) {
;     ...
;                 for (int rh = 0; rh < 2; ++rh) {
;                     const int r0 = 4 * rq + 2 * rh, r1 = r0 + 1;
; #pragma unroll
;                     for (int j = 0; j < 4; ++j) {
;                         const float x0 = v[r0][j].x * rs8[r0] * gg[j].x, x1 = v[r0][j].y * rs8[r0] * gg[j].y, x2 = v[r0][j].z * rs8[r0] * gg[j].z, x3 = v[r0][j].w * rs8[r0] * gg[j].w;
;                         const float y0 = v[r1][j].x * rs8[r1] * gg[j].x, y1 = v[r1][j].y * rs8[r1] * gg[j].y, y2 = v[r1][j].z * rs8[r1] * gg[j].z, y3 = v[r1][j].w * rs8[r1] * gg[j].w;
;                         const unsigned a0 = pk2(x0, x1), a1 = pk2(x2, x3), b0 = pk2(y0, y1), b1 = pk2(y2, y3);
;                         q8[2 * rh][j] = pk4_fp8(x0, x1, x2, x3); q8[2 * rh + 1][j] = pk4_fp8(y0, y1, y2, y3);
;                         const unsigned t0 = lodd ? a0 : b0, t1 = lodd ? a1 : b1;
;                         const unsigned g0 = (unsigned)__builtin_amdgcn_mov_dpp((int)t0, 0xB1, 0xf, 0xf, true), g1 = (unsigned)__builtin_amdgcn_mov_dpp((int)t1, 0xB1, 0xf, 0xf, true);
;                         u32x4 o; o.x = lodd ? g0 : a0; o.y = lodd ? g1 : a1; o.z = lodd ? b0 : g0; o.w = lodd ? b1 : g1;
;                         *(GAS u32x4*)(F.XN + tl_off(m0 + r0 + (lane & 1), 8 * (lane >> 1) + 256 * j, D)) = o;
;                         __builtin_amdgcn_sched_barrier(0);
;                     }
	v_mov_b32_dpp v234, v234 quad_perm:[1,0,3,2] row_mask:0xf bank_mask:0xf bound_ctrl:1
	v_lshl_add_u64 v[128:129], s[62:63], 0, v[128:129]
	v_cndmask_b32_e64 v237, v233, v234, s[4:5]
	v_cndmask_b32_e64 v236, v218, v219, s[4:5]
	v_cndmask_b32_e64 v235, v234, v214, s[4:5]
	v_cndmask_b32_e64 v234, v219, v216, s[4:5]
	v_lshl_add_u64 v[218:219], v[128:129], 0, v[148:149]
	v_lshlrev_b32_e32 v152, 1, v152
	v_lshl_add_u64 v[218:219], v[218:219], 0, v[152:153]
	global_store_dwordx4 v[218:219], v[234:237], off sc1
	v_mov_b32_e32 v218, v68
	v_mov_b32_e32 v219, v70
	v_mov_b32_e32 v234, v69
	v_mov_b32_e32 v235, v71
	v_pk_mul_f32 v[218:219], v[218:219], v[210:211] op_sel_hi:[1,0]
	v_pk_mul_f32 v[234:235], v[234:235], v[210:211] op_sel_hi:[1,0]
	v_pk_mul_f32 v[218:219], v[218:219], v[140:141]
	v_pk_mul_f32 v[234:235], v[234:235], v[138:139]
	v_mov_b32_e32 v247, v153
	v_cvt_pk_fp8_f32 v247, v218, v234
	v_and_b32_sdwa v246, v234, v226 dst_sel:DWORD dst_unused:UNUSED_PAD src0_sel:WORD_1 src1_sel:DWORD
	v_mov_b32_e32 v236, v104
	v_mov_b32_e32 v237, v106
	v_mov_b32_e32 v238, v105
	v_mov_b32_e32 v239, v107
	v_and_b32_sdwa v216, v218, v226 dst_sel:DWORD dst_unused:UNUSED_PAD src0_sel:WORD_1 src1_sel:DWORD
	v_add3_u32 v246, v234, v246, s96
	v_pk_mul_f32 v[236:237], v[236:237], v[212:213] op_sel_hi:[1,0]
	v_pk_mul_f32 v[238:239], v[238:239], v[212:213] op_sel_hi:[1,0]
	v_and_b32_sdwa v214, v219, v226 dst_sel:DWORD dst_unused:UNUSED_PAD src0_sel:WORD_1 src1_sel:DWORD
	v_add3_u32 v216, v218, v216, s96
	v_and_b32_sdwa v233, v235, v226 dst_sel:DWORD dst_unused:UNUSED_PAD src0_sel:WORD_1 src1_sel:DWORD
	v_and_b32_e32 v218, 0xffff0000, v246
	v_add3_u32 v214, v219, v214, s96
	v_add3_u32 v233, v235, v233, s96
	v_or_b32_sdwa v216, v218, v216 dst_sel:DWORD dst_unused:UNUSED_PAD src0_sel:DWORD src1_sel:WORD_1
	v_cvt_pk_fp8_f32 v247, v219, v235 op_sel:[0,0,1]
	v_pk_mul_f32 v[218:219], v[236:237], v[140:141]
	v_pk_mul_f32 v[234:235], v[238:239], v[138:139]
	v_mov_b32_e32 v246, v153
	v_and_b32_e32 v233, 0xffff0000, v233
	v_and_b32_sdwa v237, v235, v226 dst_sel:DWORD dst_unused:UNUSED_PAD src0_sel:WORD_1 src1_sel:DWORD
	v_and_b32_sdwa v238, v234, v226 dst_sel:DWORD dst_unused:UNUSED_PAD src0_sel:WORD_1 src1_sel:DWORD
	v_cvt_pk_fp8_f32 v246, v218, v234
	v_or_b32_sdwa v214, v233, v214 dst_sel:DWORD dst_unused:UNUSED_PAD src0_sel:DWORD src1_sel:WORD_1
	v_and_b32_sdwa v233, v219, v226 dst_sel:DWORD dst_unused:UNUSED_PAD src0_sel:WORD_1 src1_sel:DWORD
	v_and_b32_sdwa v236, v218, v226 dst_sel:DWORD dst_unused:UNUSED_PAD src0_sel:WORD_1 src1_sel:DWORD
	v_add3_u32 v237, v235, v237, s96
	v_add3_u32 v238, v234, v238, s96
	v_add3_u32 v236, v218, v236, s96
	v_add3_u32 v233, v219, v233, s96
	v_and_b32_e32 v237, 0xffff0000, v237
	v_and_b32_e32 v218, 0xffff0000, v238
	v_or_b32_sdwa v233, v237, v233 dst_sel:DWORD dst_unused:UNUSED_PAD src0_sel:DWORD src1_sel:WORD_1
	v_or_b32_sdwa v218, v218, v236 dst_sel:DWORD dst_unused:UNUSED_PAD src0_sel:DWORD src1_sel:WORD_1
	v_cvt_pk_fp8_f32 v246, v219, v235 op_sel:[0,0,1]
	v_cndmask_b32_e64 v219, v216, v218, s[4:5]
	v_cndmask_b32_e64 v234, v214, v233, s[4:5]
	s_nop 0
	v_mov_b32_dpp v219, v219 quad_perm:[1,0,3,2] row_mask:0xf bank_mask:0xf bound_ctrl:1
	v_mov_b32_dpp v234, v234 quad_perm:[1,0,3,2] row_mask:0xf bank_mask:0xf bound_ctrl:1
	v_cndmask_b32_e64 v237, v233, v234, s[4:5]
	v_cndmask_b32_e64 v236, v218, v219, s[4:5]
	v_cndmask_b32_e64 v235, v234, v214, s[4:5]
	v_cndmask_b32_e64 v234, v219, v216, s[4:5]
	v_lshl_add_u64 v[218:219], v[128:129], 0, v[154:155]
	v_lshl_add_u64 v[218:219], v[218:219], 0, v[152:153]
	global_store_dwordx4 v[218:219], v[234:237], off sc1
	v_mov_b32_e32 v218, v64
	v_mov_b32_e32 v219, v66
	v_mov_b32_e32 v234, v65
	v_mov_b32_e32 v235, v67
	v_pk_mul_f32 v[218:219], v[218:219], v[210:211] op_sel_hi:[1,0]
	v_pk_mul_f32 v[234:235], v[234:235], v[210:211] op_sel_hi:[1,0]
	v_pk_mul_f32 v[218:219], v[218:219], v[136:137]
	v_pk_mul_f32 v[234:235], v[234:235], v[134:135]
	v_mov_b32_e32 v249, v153
	v_cvt_pk_fp8_f32 v249, v218, v234
	v_and_b32_sdwa v248, v234, v226 dst_sel:DWORD dst_unused:UNUSED_PAD src0_sel:WORD_1 src1_sel:DWORD
	v_mov_b32_e32 v236, v100
	v_mov_b32_e32 v237, v102
	v_mov_b32_e32 v238, v101
	v_mov_b32_e32 v239, v103
	v_and_b32_sdwa v216, v218, v226 dst_sel:DWORD dst_unused:UNUSED_PAD src0_sel:WORD_1 src1_sel:DWORD
	v_add3_u32 v248, v234, v248, s96
	v_pk_mul_f32 v[236:237], v[236:237], v[212:213] op_sel_hi:[1,0]
	v_pk_mul_f32 v[238:239], v[238:239], v[212:213] op_sel_hi:[1,0]
	v_and_b32_sdwa v214, v219, v226 dst_sel:DWORD dst_unused:UNUSED_PAD src0_sel:WORD_1 src1_sel:DWORD
	v_add3_u32 v216, v218, v216, s96
	v_and_b32_sdwa v233, v235, v226 dst_sel:DWORD dst_unused:UNUSED_PAD src0_sel:WORD_1 src1_sel:DWORD
	v_and_b32_e32 v218, 0xffff0000, v248
	v_add3_u32 v214, v219, v214, s96
	v_add3_u32 v233, v235, v233, s96
	v_or_b32_sdwa v216, v218, v216 dst_sel:DWORD dst_unused:UNUSED_PAD src0_sel:DWORD src1_sel:WORD_1
	v_cvt_pk_fp8_f32 v249, v219, v235 op_sel:[0,0,1]
	v_pk_mul_f32 v[218:219], v[236:237], v[136:137]
	v_pk_mul_f32 v[234:235], v[238:239], v[134:135]
	v_mov_b32_e32 v248, v153
	v_and_b32_e32 v233, 0xffff0000, v233
	v_and_b32_sdwa v237, v235, v226 dst_sel:DWORD dst_unused:UNUSED_PAD src0_sel:WORD_1 src1_sel:DWORD
	v_and_b32_sdwa v238, v234, v226 dst_sel:DWORD dst_unused:UNUSED_PAD src0_sel:WORD_1 src1_sel:DWORD
	v_cvt_pk_fp8_f32 v248, v218, v234
	v_or_b32_sdwa v214, v233, v214 dst_sel:DWORD dst_unused:UNUSED_PAD src0_sel:DWORD src1_sel:WORD_1
	v_and_b32_sdwa v233, v219, v226 dst_sel:DWORD dst_unused:UNUSED_PAD src0_sel:WORD_1 src1_sel:DWORD
	v_and_b32_sdwa v236, v218, v226 dst_sel:DWORD dst_unused:UNUSED_PAD src0_sel:WORD_1 src1_sel:DWORD
; #define GAS __attribute__((address_space(1)))
; __device__ __forceinline__ void p0_prologue(Frame& F) {
;     ...
;                     for (int j = 0; j < 4; ++j) {
;                         const float x0 = v[r0][j].x * rs8[r0] * gg[j].x, x1 = v[r0][j].y * rs8[r0] * gg[j].y, x2 = v[r0][j].z * rs8[r0] * gg[j].z, x3 = v[r0][j].w * rs8[r0] * gg[j].w;
;                         const float y0 = v[r1][j].x * rs8[r1] * gg[j].x, y1 = v[r1][j].y * rs8[r1] * gg[j].y, y2 = v[r1][j].z * rs8[r1] * gg[j].z, y3 = v[r1][j].w * rs8[r1] * gg[j].w;
;                         const unsigned a0 = pk2(x0, x1), a1 = pk2(x2, x3), b0 = pk2(y0, y1), b1 = pk2(y2, y3);
;                         q8[2 * rh][j] = pk4_fp8(x0, x1, x2, x3); q8[2 * rh + 1][j] = pk4_fp8(y0, y1, y2, y3);
;                         const unsigned t0 = lodd ? a0 : b0, t1 = lodd ? a1 : b1;
;                         const unsigned g0 = (unsigned)__builtin_amdgcn_mov_dpp((int)t0, 0xB1, 0xf, 0xf, true), g1 = (unsigned)__builtin_amdgcn_mov_dpp((int)t1, 0xB1, 0xf, 0xf, true);
;                         u32x4 o; o.x = lodd ? g0 : a0; o.y = lodd ? g1 : a1; o.z = lodd ? b0 : g0; o.w = lodd ? b1 : g1;
;                         *(GAS u32x4*)(F.XN + tl_off(m0 + r0 + (lane & 1), 8 * (lane >> 1) + 256 * j, D)) = o;
;                         __builtin_amdgcn_sched_barrier(0);
;                     }
;     ...
;                 for (int j = 0; j < 4; ++j) {
;                     const unsigned t0 = q8[0][j], t1 = q8[1][j], t2 = q8[2][j], t3 = q8[3][j];
;                     const unsigned sA = lodd ? t0 : t1, sB = lodd ? t2 : t3;
;                     const unsigned rA = (unsigned)__builtin_amdgcn_mov_dpp((int)sA, 0xB1, 0xf, 0xf, true), rB = (unsigned)__builtin_amdgcn_mov_dpp((int)sB, 0xB1, 0xf, 0xf, true);
;                     const unsigned u0 = lodd ? rA : t0, u1 = lodd ? t1 : rA;
;                     const unsigned w0 = lodd ? rB : t2, w1 = lodd ? t3 : rB;
;                     const unsigned c0 = lhi ? u0 : w0, c1 = lhi ? u1 : w1;
;                     const unsigned d0 = (unsigned)__builtin_amdgcn_mov_dpp((int)c0, 0x4E, 0xf, 0xf, true), d1 = (unsigned)__builtin_amdgcn_mov_dpp((int)c1, 0x4E, 0xf, 0xf, true);
;                     u32x4 o; o.x = lhi ? d0 : u0; o.y = lhi ? d1 : u1; o.z = lhi ? w0 : d0; o.w = lhi ? w1 : d1;
;                     *(GAS u32x4*)(F.XN8 + tl8_off(m0 + 4 * rq + (lane & 3), 16 * (lane >> 2) + 256 * j, D)) = o;
	v_add3_u32 v237, v235, v237, s96
	v_add3_u32 v238, v234, v238, s96
	v_add3_u32 v236, v218, v236, s96
	v_add3_u32 v233, v219, v233, s96
	v_and_b32_e32 v237, 0xffff0000, v237
	v_and_b32_e32 v218, 0xffff0000, v238
	v_or_b32_sdwa v233, v237, v233 dst_sel:DWORD dst_unused:UNUSED_PAD src0_sel:DWORD src1_sel:WORD_1
	v_or_b32_sdwa v218, v218, v236 dst_sel:DWORD dst_unused:UNUSED_PAD src0_sel:DWORD src1_sel:WORD_1
	v_cvt_pk_fp8_f32 v248, v219, v235 op_sel:[0,0,1]
	v_cndmask_b32_e64 v219, v216, v218, s[4:5]
	v_cndmask_b32_e64 v234, v214, v233, s[4:5]
	s_nop 0
	v_mov_b32_dpp v219, v219 quad_perm:[1,0,3,2] row_mask:0xf bank_mask:0xf bound_ctrl:1
	v_mov_b32_dpp v234, v234 quad_perm:[1,0,3,2] row_mask:0xf bank_mask:0xf bound_ctrl:1
	v_cndmask_b32_e64 v237, v233, v234, s[4:5]
	v_cndmask_b32_e64 v236, v218, v219, s[4:5]
	v_cndmask_b32_e64 v235, v234, v214, s[4:5]
	v_cndmask_b32_e64 v234, v219, v216, s[4:5]
	v_lshl_add_u64 v[218:219], v[128:129], 0, v[156:157]
	v_lshl_add_u64 v[218:219], v[218:219], 0, v[152:153]
	global_store_dwordx4 v[218:219], v[234:237], off sc1
	v_mov_b32_e32 v218, v76
	v_mov_b32_e32 v219, v78
	v_mov_b32_e32 v234, v77
	v_mov_b32_e32 v235, v79
	v_pk_mul_f32 v[218:219], v[218:219], v[210:211] op_sel_hi:[1,0]
	v_pk_mul_f32 v[234:235], v[234:235], v[210:211] op_sel_hi:[1,0]
	v_pk_mul_f32 v[218:219], v[218:219], v[132:133]
	v_pk_mul_f32 v[234:235], v[234:235], v[130:131]
	v_mov_b32_e32 v250, v153
	v_cvt_pk_fp8_f32 v250, v218, v234
	v_mov_b32_e32 v236, v108
	v_mov_b32_e32 v237, v110
	v_mov_b32_e32 v238, v109
	v_mov_b32_e32 v239, v111
	v_pk_mul_f32 v[236:237], v[236:237], v[212:213] op_sel_hi:[1,0]
	v_pk_mul_f32 v[238:239], v[238:239], v[212:213] op_sel_hi:[1,0]
	v_and_b32_sdwa v210, v219, v226 dst_sel:DWORD dst_unused:UNUSED_PAD src0_sel:WORD_1 src1_sel:DWORD
	v_and_b32_sdwa v212, v218, v226 dst_sel:DWORD dst_unused:UNUSED_PAD src0_sel:WORD_1 src1_sel:DWORD
	v_and_b32_sdwa v214, v235, v226 dst_sel:DWORD dst_unused:UNUSED_PAD src0_sel:WORD_1 src1_sel:DWORD
	v_and_b32_sdwa v216, v234, v226 dst_sel:DWORD dst_unused:UNUSED_PAD src0_sel:WORD_1 src1_sel:DWORD
	v_add3_u32 v212, v218, v212, s96
	v_add3_u32 v210, v219, v210, s96
	v_add3_u32 v214, v235, v214, s96
	v_add3_u32 v216, v234, v216, s96
	v_cvt_pk_fp8_f32 v250, v219, v235 op_sel:[0,0,1]
	v_pk_mul_f32 v[218:219], v[236:237], v[132:133]
	v_pk_mul_f32 v[234:235], v[238:239], v[130:131]
	v_mov_b32_e32 v238, v153
	v_and_b32_e32 v214, 0xffff0000, v214
	v_and_b32_e32 v216, 0xffff0000, v216
	v_and_b32_sdwa v233, v235, v226 dst_sel:DWORD dst_unused:UNUSED_PAD src0_sel:WORD_1 src1_sel:DWORD
	v_and_b32_sdwa v236, v234, v226 dst_sel:DWORD dst_unused:UNUSED_PAD src0_sel:WORD_1 src1_sel:DWORD
	v_cvt_pk_fp8_f32 v238, v218, v234
	v_or_b32_sdwa v210, v214, v210 dst_sel:DWORD dst_unused:UNUSED_PAD src0_sel:DWORD src1_sel:WORD_1
	v_or_b32_sdwa v212, v216, v212 dst_sel:DWORD dst_unused:UNUSED_PAD src0_sel:DWORD src1_sel:WORD_1
	v_and_b32_sdwa v214, v219, v226 dst_sel:DWORD dst_unused:UNUSED_PAD src0_sel:WORD_1 src1_sel:DWORD
	v_and_b32_sdwa v216, v218, v226 dst_sel:DWORD dst_unused:UNUSED_PAD src0_sel:WORD_1 src1_sel:DWORD
	v_add3_u32 v233, v235, v233, s96
	v_add3_u32 v236, v234, v236, s96
	v_add3_u32 v216, v218, v216, s96
	v_add3_u32 v214, v219, v214, s96
	v_and_b32_e32 v233, 0xffff0000, v233
	v_and_b32_e32 v218, 0xffff0000, v236
	v_or_b32_sdwa v214, v233, v214 dst_sel:DWORD dst_unused:UNUSED_PAD src0_sel:DWORD src1_sel:WORD_1
	v_or_b32_sdwa v216, v218, v216 dst_sel:DWORD dst_unused:UNUSED_PAD src0_sel:DWORD src1_sel:WORD_1
	v_cvt_pk_fp8_f32 v238, v219, v235 op_sel:[0,0,1]
	v_cndmask_b32_e64 v218, v212, v216, s[4:5]
	v_cndmask_b32_e64 v219, v210, v214, s[4:5]
	v_lshl_add_u64 v[128:129], v[128:129], 0, v[158:159]
	v_mov_b32_dpp v218, v218 quad_perm:[1,0,3,2] row_mask:0xf bank_mask:0xf bound_ctrl:1
	v_mov_b32_dpp v219, v219 quad_perm:[1,0,3,2] row_mask:0xf bank_mask:0xf bound_ctrl:1
	v_cndmask_b32_e64 v237, v214, v219, s[4:5]
	v_cndmask_b32_e64 v236, v216, v218, s[4:5]
	v_cndmask_b32_e64 v235, v219, v210, s[4:5]
	v_cndmask_b32_e64 v234, v218, v212, s[4:5]
	v_lshl_add_u64 v[128:129], v[128:129], 0, v[152:153]
	global_store_dwordx4 v[128:129], v[234:237], off sc1
	v_cndmask_b32_e64 v210, v229, v230, s[4:5]
	v_cndmask_b32_e64 v212, v245, v241, s[4:5]
	v_ashrrev_i32_e32 v128, 4, v227
	v_mov_b32_dpp v210, v210 quad_perm:[1,0,3,2] row_mask:0xf bank_mask:0xf bound_ctrl:1
	v_mov_b32_dpp v212, v212 quad_perm:[1,0,3,2] row_mask:0xf bank_mask:0xf bound_ctrl:1
	v_ashrrev_i32_e32 v129, 31, v128
	v_cndmask_b32_e64 v214, v210, v229, s[4:5]
	v_cndmask_b32_e64 v210, v230, v210, s[4:5]
	v_cndmask_b32_e64 v216, v212, v245, s[4:5]
	v_cndmask_b32_e64 v212, v241, v212, s[4:5]
	v_lshlrev_b64 v[128:129], 14, v[128:129]
	v_cndmask_b32_e64 v218, v214, v216, s[6:7]
	v_cndmask_b32_e64 v219, v210, v212, s[6:7]
	v_lshlrev_b32_e32 v152, 6, v227
	v_mov_b32_dpp v218, v218 quad_perm:[2,3,0,1] row_mask:0xf bank_mask:0xf bound_ctrl:1
	v_mov_b32_dpp v219, v219 quad_perm:[2,3,0,1] row_mask:0xf bank_mask:0xf bound_ctrl:1
	v_lshl_add_u64 v[128:129], s[64:65], 0, v[128:129]
	v_and_or_b32 v152, v152, s95, v222
	v_cndmask_b32_e64 v234, v218, v214, s[6:7]
	v_cndmask_b32_e64 v235, v219, v210, s[6:7]
	v_cndmask_b32_e64 v236, v216, v218, s[6:7]
	v_cndmask_b32_e64 v237, v212, v219, s[6:7]
	v_lshl_add_u64 v[218:219], v[128:129], 0, v[150:151]
	v_lshl_add_u64 v[218:219], v[218:219], 0, v[152:153]
	global_store_dwordx4 v[218:219], v[234:237], off sc1
	v_cndmask_b32_e64 v210, v231, v232, s[4:5]
	v_cndmask_b32_e64 v212, v247, v246, s[4:5]
	s_nop 0
	v_mov_b32_dpp v210, v210 quad_perm:[1,0,3,2] row_mask:0xf bank_mask:0xf bound_ctrl:1
; #define GAS __attribute__((address_space(1)))
; __device__ __forceinline__ void p0_prologue(Frame& F) {
;     ...
;                 for (int rh = 0; rh < 2; ++rh) {
;                     const int r0 = 4 * rq + 2 * rh, r1 = r0 + 1;
; #pragma unroll
;                     for (int j = 0; j < 4; ++j) {
;                         const float x0 = v[r0][j].x * rs8[r0] * gg[j].x, x1 = v[r0][j].y * rs8[r0] * gg[j].y, x2 = v[r0][j].z * rs8[r0] * gg[j].z, x3 = v[r0][j].w * rs8[r0] * gg[j].w;
;                         const float y0 = v[r1][j].x * rs8[r1] * gg[j].x, y1 = v[r1][j].y * rs8[r1] * gg[j].y, y2 = v[r1][j].z * rs8[r1] * gg[j].z, y3 = v[r1][j].w * rs8[r1] * gg[j].w;
;                         const unsigned a0 = pk2(x0, x1), a1 = pk2(x2, x3), b0 = pk2(y0, y1), b1 = pk2(y2, y3);
;                         q8[2 * rh][j] = pk4_fp8(x0, x1, x2, x3); q8[2 * rh + 1][j] = pk4_fp8(y0, y1, y2, y3);
;                         const unsigned t0 = lodd ? a0 : b0, t1 = lodd ? a1 : b1;
;                         const unsigned g0 = (unsigned)__builtin_amdgcn_mov_dpp((int)t0, 0xB1, 0xf, 0xf, true), g1 = (unsigned)__builtin_amdgcn_mov_dpp((int)t1, 0xB1, 0xf, 0xf, true);
;                         u32x4 o; o.x = lodd ? g0 : a0; o.y = lodd ? g1 : a1; o.z = lodd ? b0 : g0; o.w = lodd ? b1 : g1;
;     ...
;                 for (int j = 0; j < 4; ++j) {
;                     const unsigned t0 = q8[0][j], t1 = q8[1][j], t2 = q8[2][j], t3 = q8[3][j];
;                     const unsigned sA = lodd ? t0 : t1, sB = lodd ? t2 : t3;
;                     const unsigned rA = (unsigned)__builtin_amdgcn_mov_dpp((int)sA, 0xB1, 0xf, 0xf, true), rB = (unsigned)__builtin_amdgcn_mov_dpp((int)sB, 0xB1, 0xf, 0xf, true);
;                     const unsigned u0 = lodd ? rA : t0, u1 = lodd ? t1 : rA;
;                     const unsigned w0 = lodd ? rB : t2, w1 = lodd ? t3 : rB;
;                     const unsigned c0 = lhi ? u0 : w0, c1 = lhi ? u1 : w1;
;                     const unsigned d0 = (unsigned)__builtin_amdgcn_mov_dpp((int)c0, 0x4E, 0xf, 0xf, true), d1 = (unsigned)__builtin_amdgcn_mov_dpp((int)c1, 0x4E, 0xf, 0xf, true);
;                     u32x4 o; o.x = lhi ? d0 : u0; o.y = lhi ? d1 : u1; o.z = lhi ? w0 : d0; o.w = lhi ? w1 : d1;
;                     *(GAS u32x4*)(F.XN8 + tl8_off(m0 + 4 * rq + (lane & 3), 16 * (lane >> 2) + 256 * j, D)) = o;
;                     __builtin_amdgcn_sched_barrier(0);
	v_mov_b32_dpp v212, v212 quad_perm:[1,0,3,2] row_mask:0xf bank_mask:0xf bound_ctrl:1
	v_cndmask_b32_e64 v214, v210, v231, s[4:5]
	v_cndmask_b32_e64 v210, v232, v210, s[4:5]
	v_cndmask_b32_e64 v216, v212, v247, s[4:5]
	v_cndmask_b32_e64 v212, v246, v212, s[4:5]
	v_cndmask_b32_e64 v218, v214, v216, s[6:7]
	v_cndmask_b32_e64 v219, v210, v212, s[6:7]
	s_nop 0
	v_mov_b32_dpp v218, v218 quad_perm:[2,3,0,1] row_mask:0xf bank_mask:0xf bound_ctrl:1
	v_mov_b32_dpp v219, v219 quad_perm:[2,3,0,1] row_mask:0xf bank_mask:0xf bound_ctrl:1
	v_cndmask_b32_e64 v230, v218, v214, s[6:7]
	v_cndmask_b32_e64 v231, v219, v210, s[6:7]
	v_cndmask_b32_e64 v232, v216, v218, s[6:7]
	v_cndmask_b32_e64 v233, v212, v219, s[6:7]
	v_lshl_add_u64 v[218:219], v[128:129], 0, v[160:161]
	v_lshl_add_u64 v[218:219], v[218:219], 0, v[152:153]
	global_store_dwordx4 v[218:219], v[230:233], off sc1
	v_cndmask_b32_e64 v210, v243, v244, s[4:5]
	v_cndmask_b32_e64 v212, v249, v248, s[4:5]
	s_nop 0
	v_mov_b32_dpp v210, v210 quad_perm:[1,0,3,2] row_mask:0xf bank_mask:0xf bound_ctrl:1
	v_mov_b32_dpp v212, v212 quad_perm:[1,0,3,2] row_mask:0xf bank_mask:0xf bound_ctrl:1
	v_cndmask_b32_e64 v214, v210, v243, s[4:5]
	v_cndmask_b32_e64 v210, v244, v210, s[4:5]
	v_cndmask_b32_e64 v216, v212, v249, s[4:5]
	v_cndmask_b32_e64 v212, v248, v212, s[4:5]
	v_cndmask_b32_e64 v218, v214, v216, s[6:7]
	v_cndmask_b32_e64 v219, v210, v212, s[6:7]
	s_nop 0
	v_mov_b32_dpp v218, v218 quad_perm:[2,3,0,1] row_mask:0xf bank_mask:0xf bound_ctrl:1
	v_mov_b32_dpp v219, v219 quad_perm:[2,3,0,1] row_mask:0xf bank_mask:0xf bound_ctrl:1
	v_cndmask_b32_e64 v230, v218, v214, s[6:7]
	v_cndmask_b32_e64 v231, v219, v210, s[6:7]
	v_cndmask_b32_e64 v232, v216, v218, s[6:7]
	v_cndmask_b32_e64 v233, v212, v219, s[6:7]
	v_lshl_add_u64 v[218:219], v[128:129], 0, v[162:163]
	v_lshl_add_u64 v[218:219], v[218:219], 0, v[152:153]
	global_store_dwordx4 v[218:219], v[230:233], off sc1
	v_cndmask_b32_e64 v210, v242, v240, s[4:5]
	v_cndmask_b32_e64 v212, v250, v238, s[4:5]
	v_lshl_add_u64 v[128:129], v[128:129], 0, v[164:165]
	v_mov_b32_dpp v210, v210 quad_perm:[1,0,3,2] row_mask:0xf bank_mask:0xf bound_ctrl:1
	v_mov_b32_dpp v212, v212 quad_perm:[1,0,3,2] row_mask:0xf bank_mask:0xf bound_ctrl:1
	v_cndmask_b32_e64 v214, v210, v242, s[4:5]
	v_cndmask_b32_e64 v210, v240, v210, s[4:5]
	v_cndmask_b32_e64 v216, v212, v250, s[4:5]
	v_cndmask_b32_e64 v212, v238, v212, s[4:5]
	v_cndmask_b32_e64 v218, v214, v216, s[6:7]
	v_cndmask_b32_e64 v219, v210, v212, s[6:7]
	v_lshl_add_u64 v[128:129], v[128:129], 0, v[152:153]
	v_mov_b32_dpp v218, v218 quad_perm:[2,3,0,1] row_mask:0xf bank_mask:0xf bound_ctrl:1
	v_mov_b32_dpp v219, v219 quad_perm:[2,3,0,1] row_mask:0xf bank_mask:0xf bound_ctrl:1
	v_cndmask_b32_e64 v230, v218, v214, s[6:7]
	v_cndmask_b32_e64 v231, v219, v210, s[6:7]
	v_cndmask_b32_e64 v232, v216, v218, s[6:7]
	v_cndmask_b32_e64 v233, v212, v219, s[6:7]
	global_store_dwordx4 v[128:129], v[230:233], off sc1
	v_add_u32_e32 v152, 4, v228
	v_ashrrev_i32_e32 v128, 4, v152
	v_ashrrev_i32_e32 v129, 31, v128
	v_lshlrev_b64 v[218:219], 15, v[128:129]
	v_mov_b32_e32 v128, v124
	v_mov_b32_e32 v129, v126
	v_pk_mul_f32 v[128:129], v[128:129], v[204:205] op_sel_hi:[1,0]
	v_mov_b32_e32 v230, v125
	v_mov_b32_e32 v231, v127
	v_pk_mul_f32 v[230:231], v[230:231], v[204:205] op_sel_hi:[1,0]
	v_pk_mul_f32 v[236:237], v[128:129], v[208:209]
	v_pk_mul_f32 v[230:231], v[230:231], v[142:143]
	v_and_b32_sdwa v128, v237, v226 dst_sel:DWORD dst_unused:UNUSED_PAD src0_sel:WORD_1 src1_sel:DWORD
	v_add3_u32 v210, v237, v128, s96
	v_and_b32_sdwa v128, v231, v226 dst_sel:DWORD dst_unused:UNUSED_PAD src0_sel:WORD_1 src1_sel:DWORD
	v_add3_u32 v128, v231, v128, s96
	v_and_b32_e32 v214, 0xffff0000, v128
	v_mov_b32_e32 v128, v153
	v_cvt_pk_fp8_f32 v128, v236, v230
	v_mov_b32_e32 v232, v40
	v_mov_b32_e32 v233, v42
	v_and_b32_sdwa v212, v230, v226 dst_sel:DWORD dst_unused:UNUSED_PAD src0_sel:WORD_1 src1_sel:DWORD
	v_pk_mul_f32 v[232:233], v[232:233], v[206:207] op_sel_hi:[1,0]
	v_mov_b32_e32 v234, v41
	v_mov_b32_e32 v235, v43
	v_and_b32_sdwa v129, v236, v226 dst_sel:DWORD dst_unused:UNUSED_PAD src0_sel:WORD_1 src1_sel:DWORD
	v_add3_u32 v212, v230, v212, s96
	v_pk_mul_f32 v[234:235], v[234:235], v[206:207] op_sel_hi:[1,0]
	v_add3_u32 v129, v236, v129, s96
	v_and_b32_e32 v212, 0xffff0000, v212
	v_cvt_pk_fp8_f32 v128, v237, v231 op_sel:[0,0,1]
	v_pk_mul_f32 v[230:231], v[232:233], v[208:209]
	v_or_b32_sdwa v212, v212, v129 dst_sel:DWORD dst_unused:UNUSED_PAD src0_sel:DWORD src1_sel:WORD_1
	v_pk_mul_f32 v[232:233], v[234:235], v[142:143]
	v_and_b32_sdwa v129, v231, v226 dst_sel:DWORD dst_unused:UNUSED_PAD src0_sel:WORD_1 src1_sel:DWORD
	v_add3_u32 v216, v231, v129, s96
	v_and_b32_sdwa v129, v233, v226 dst_sel:DWORD dst_unused:UNUSED_PAD src0_sel:WORD_1 src1_sel:DWORD
	v_and_b32_sdwa v229, v232, v226 dst_sel:DWORD dst_unused:UNUSED_PAD src0_sel:WORD_1 src1_sel:DWORD
	v_add3_u32 v129, v233, v129, s96
	v_or_b32_sdwa v210, v214, v210 dst_sel:DWORD dst_unused:UNUSED_PAD src0_sel:DWORD src1_sel:WORD_1
	v_and_b32_sdwa v214, v230, v226 dst_sel:DWORD dst_unused:UNUSED_PAD src0_sel:WORD_1 src1_sel:DWORD
	v_add3_u32 v229, v232, v229, s96
	v_and_b32_e32 v234, 0xffff0000, v129
	v_mov_b32_e32 v129, v153
	v_add3_u32 v214, v230, v214, s96
	v_cvt_pk_fp8_f32 v129, v230, v232
	v_and_b32_e32 v229, 0xffff0000, v229
	v_lshlrev_b32_e32 v152, 5, v152
	v_or_b32_sdwa v216, v234, v216 dst_sel:DWORD dst_unused:UNUSED_PAD src0_sel:DWORD src1_sel:WORD_1
	v_or_b32_sdwa v214, v229, v214 dst_sel:DWORD dst_unused:UNUSED_PAD src0_sel:DWORD src1_sel:WORD_1
	v_and_or_b32 v152, v152, s54, v220
	v_cndmask_b32_e64 v229, v212, v214, s[4:5]
; #define GAS __attribute__((address_space(1)))
; __host__ __device__ __forceinline__ size_t tl_off(int row, int k, int K) { return ((((size_t)(row >> 4) * (size_t)(K >> 5)) + (size_t)(k >> 5)) << 9) + (size_t)((row & 15) * 32 + (k & 31)); }
; __device__ __forceinline__ unsigned pk2(float lo, float hi) { return f2bf(lo) | (f2bf(hi) << 16); }
; __device__ __forceinline__ void p0_prologue(Frame& F) {
;     ...
;                 for (int rh = 0; rh < 2; ++rh) {
;                     const int r0 = 4 * rq + 2 * rh, r1 = r0 + 1;
; #pragma unroll
;                     for (int j = 0; j < 4; ++j) {
;                         const float x0 = v[r0][j].x * rs8[r0] * gg[j].x, x1 = v[r0][j].y * rs8[r0] * gg[j].y, x2 = v[r0][j].z * rs8[r0] * gg[j].z, x3 = v[r0][j].w * rs8[r0] * gg[j].w;
;                         const float y0 = v[r1][j].x * rs8[r1] * gg[j].x, y1 = v[r1][j].y * rs8[r1] * gg[j].y, y2 = v[r1][j].z * rs8[r1] * gg[j].z, y3 = v[r1][j].w * rs8[r1] * gg[j].w;
;                         const unsigned a0 = pk2(x0, x1), a1 = pk2(x2, x3), b0 = pk2(y0, y1), b1 = pk2(y2, y3);
;                         q8[2 * rh][j] = pk4_fp8(x0, x1, x2, x3); q8[2 * rh + 1][j] = pk4_fp8(y0, y1, y2, y3);
;                         const unsigned t0 = lodd ? a0 : b0, t1 = lodd ? a1 : b1;
;                         const unsigned g0 = (unsigned)__builtin_amdgcn_mov_dpp((int)t0, 0xB1, 0xf, 0xf, true), g1 = (unsigned)__builtin_amdgcn_mov_dpp((int)t1, 0xB1, 0xf, 0xf, true);
;                         u32x4 o; o.x = lodd ? g0 : a0; o.y = lodd ? g1 : a1; o.z = lodd ? b0 : g0; o.w = lodd ? b1 : g1;
;                         *(GAS u32x4*)(F.XN + tl_off(m0 + r0 + (lane & 1), 8 * (lane >> 1) + 256 * j, D)) = o;
;                         __builtin_amdgcn_sched_barrier(0);
;                     }
	v_cndmask_b32_e64 v230, v210, v216, s[4:5]
	v_lshl_add_u64 v[218:219], s[62:63], 0, v[218:219]
	v_mov_b32_dpp v229, v229 quad_perm:[1,0,3,2] row_mask:0xf bank_mask:0xf bound_ctrl:1
	v_mov_b32_dpp v230, v230 quad_perm:[1,0,3,2] row_mask:0xf bank_mask:0xf bound_ctrl:1
	v_lshl_add_u64 v[234:235], v[218:219], 0, v[148:149]
	v_lshlrev_b32_e32 v152, 1, v152
	v_cvt_pk_fp8_f32 v129, v231, v233 op_sel:[0,0,1]
	v_cndmask_b32_e64 v233, v216, v230, s[4:5]
	v_cndmask_b32_e64 v232, v214, v229, s[4:5]
	v_cndmask_b32_e64 v231, v230, v210, s[4:5]
	v_cndmask_b32_e64 v230, v229, v212, s[4:5]
	v_lshl_add_u64 v[234:235], v[234:235], 0, v[152:153]
	global_store_dwordx4 v[234:235], v[230:233], off sc1
	s_nop 1
	v_mov_b32_e32 v230, v120
	v_mov_b32_e32 v231, v122
	v_pk_mul_f32 v[230:231], v[230:231], v[204:205] op_sel_hi:[1,0]
	v_mov_b32_e32 v232, v121
	v_mov_b32_e32 v233, v123
	v_pk_mul_f32 v[232:233], v[232:233], v[204:205] op_sel_hi:[1,0]
	v_pk_mul_f32 v[230:231], v[230:231], v[140:141]
	v_pk_mul_f32 v[232:233], v[232:233], v[138:139]
	v_and_b32_sdwa v210, v231, v226 dst_sel:DWORD dst_unused:UNUSED_PAD src0_sel:WORD_1 src1_sel:DWORD
	v_add3_u32 v214, v231, v210, s96
	v_and_b32_sdwa v210, v233, v226 dst_sel:DWORD dst_unused:UNUSED_PAD src0_sel:WORD_1 src1_sel:DWORD
	v_add3_u32 v210, v233, v210, s96
	v_and_b32_e32 v229, 0xffff0000, v210
	v_mov_b32_e32 v210, v153
	v_cvt_pk_fp8_f32 v210, v230, v232
	v_mov_b32_e32 v234, v24
	v_mov_b32_e32 v235, v26
	v_and_b32_sdwa v216, v232, v226 dst_sel:DWORD dst_unused:UNUSED_PAD src0_sel:WORD_1 src1_sel:DWORD
	v_pk_mul_f32 v[234:235], v[234:235], v[206:207] op_sel_hi:[1,0]
	v_mov_b32_e32 v236, v25
	v_mov_b32_e32 v237, v27
	v_and_b32_sdwa v212, v230, v226 dst_sel:DWORD dst_unused:UNUSED_PAD src0_sel:WORD_1 src1_sel:DWORD
	v_add3_u32 v216, v232, v216, s96
	v_pk_mul_f32 v[236:237], v[236:237], v[206:207] op_sel_hi:[1,0]
	v_add3_u32 v212, v230, v212, s96
	v_and_b32_e32 v216, 0xffff0000, v216
	v_cvt_pk_fp8_f32 v210, v231, v233 op_sel:[0,0,1]
	v_pk_mul_f32 v[230:231], v[234:235], v[140:141]
	v_or_b32_sdwa v216, v216, v212 dst_sel:DWORD dst_unused:UNUSED_PAD src0_sel:DWORD src1_sel:WORD_1
	v_pk_mul_f32 v[232:233], v[236:237], v[138:139]
	v_and_b32_sdwa v212, v231, v226 dst_sel:DWORD dst_unused:UNUSED_PAD src0_sel:WORD_1 src1_sel:DWORD
	v_add3_u32 v234, v231, v212, s96
	v_and_b32_sdwa v212, v233, v226 dst_sel:DWORD dst_unused:UNUSED_PAD src0_sel:WORD_1 src1_sel:DWORD
	v_add3_u32 v212, v233, v212, s96
	v_and_b32_e32 v236, 0xffff0000, v212
	v_mov_b32_e32 v212, v153
	v_and_b32_sdwa v235, v232, v226 dst_sel:DWORD dst_unused:UNUSED_PAD src0_sel:WORD_1 src1_sel:DWORD
	v_cvt_pk_fp8_f32 v212, v230, v232
	v_or_b32_sdwa v214, v229, v214 dst_sel:DWORD dst_unused:UNUSED_PAD src0_sel:DWORD src1_sel:WORD_1
	v_and_b32_sdwa v229, v230, v226 dst_sel:DWORD dst_unused:UNUSED_PAD src0_sel:WORD_1 src1_sel:DWORD
	v_add3_u32 v235, v232, v235, s96
	v_add3_u32 v229, v230, v229, s96
	v_and_b32_e32 v230, 0xffff0000, v235
	v_or_b32_sdwa v232, v236, v234 dst_sel:DWORD dst_unused:UNUSED_PAD src0_sel:DWORD src1_sel:WORD_1
	v_or_b32_sdwa v229, v230, v229 dst_sel:DWORD dst_unused:UNUSED_PAD src0_sel:DWORD src1_sel:WORD_1
	v_cvt_pk_fp8_f32 v212, v231, v233 op_sel:[0,0,1]
	v_cndmask_b32_e64 v230, v216, v229, s[4:5]
	v_cndmask_b32_e64 v231, v214, v232, s[4:5]
	v_lshl_add_u64 v[234:235], v[218:219], 0, v[154:155]
	v_mov_b32_dpp v230, v230 quad_perm:[1,0,3,2] row_mask:0xf bank_mask:0xf bound_ctrl:1
	v_mov_b32_dpp v231, v231 quad_perm:[1,0,3,2] row_mask:0xf bank_mask:0xf bound_ctrl:1
	v_cndmask_b32_e64 v233, v232, v231, s[4:5]
	v_cndmask_b32_e64 v232, v229, v230, s[4:5]
	v_cndmask_b32_e64 v231, v231, v214, s[4:5]
	v_cndmask_b32_e64 v230, v230, v216, s[4:5]
	v_lshl_add_u64 v[234:235], v[234:235], 0, v[152:153]
	global_store_dwordx4 v[234:235], v[230:233], off sc1
	s_nop 1
	v_mov_b32_e32 v230, v116
	v_mov_b32_e32 v231, v118
	v_mov_b32_e32 v232, v117
	v_mov_b32_e32 v233, v119
	v_pk_mul_f32 v[230:231], v[230:231], v[204:205] op_sel_hi:[1,0]
	v_pk_mul_f32 v[232:233], v[232:233], v[204:205] op_sel_hi:[1,0]
	v_pk_mul_f32 v[230:231], v[230:231], v[136:137]
	v_pk_mul_f32 v[232:233], v[232:233], v[134:135]
	v_mov_b32_e32 v239, v153
	v_cvt_pk_fp8_f32 v239, v230, v232
	v_and_b32_sdwa v238, v232, v226 dst_sel:DWORD dst_unused:UNUSED_PAD src0_sel:WORD_1 src1_sel:DWORD
	v_mov_b32_e32 v234, v20
	v_mov_b32_e32 v235, v22
	v_mov_b32_e32 v236, v21
	v_mov_b32_e32 v237, v23
	v_and_b32_sdwa v216, v230, v226 dst_sel:DWORD dst_unused:UNUSED_PAD src0_sel:WORD_1 src1_sel:DWORD
	v_add3_u32 v238, v232, v238, s96
	v_pk_mul_f32 v[234:235], v[234:235], v[206:207] op_sel_hi:[1,0]
	v_pk_mul_f32 v[236:237], v[236:237], v[206:207] op_sel_hi:[1,0]
	v_and_b32_sdwa v214, v231, v226 dst_sel:DWORD dst_unused:UNUSED_PAD src0_sel:WORD_1 src1_sel:DWORD
	v_add3_u32 v216, v230, v216, s96
	v_and_b32_sdwa v229, v233, v226 dst_sel:DWORD dst_unused:UNUSED_PAD src0_sel:WORD_1 src1_sel:DWORD
	v_and_b32_e32 v230, 0xffff0000, v238
	v_add3_u32 v214, v231, v214, s96
	v_add3_u32 v229, v233, v229, s96
	v_or_b32_sdwa v216, v230, v216 dst_sel:DWORD dst_unused:UNUSED_PAD src0_sel:DWORD src1_sel:WORD_1
	v_cvt_pk_fp8_f32 v239, v231, v233 op_sel:[0,0,1]
	v_pk_mul_f32 v[230:231], v[234:235], v[136:137]
	v_pk_mul_f32 v[232:233], v[236:237], v[134:135]
	v_mov_b32_e32 v238, v153
	v_and_b32_sdwa v236, v232, v226 dst_sel:DWORD dst_unused:UNUSED_PAD src0_sel:WORD_1 src1_sel:DWORD
	v_cvt_pk_fp8_f32 v238, v230, v232
	v_and_b32_e32 v229, 0xffff0000, v229
	v_and_b32_sdwa v234, v230, v226 dst_sel:DWORD dst_unused:UNUSED_PAD src0_sel:WORD_1 src1_sel:DWORD
	v_and_b32_sdwa v235, v233, v226 dst_sel:DWORD dst_unused:UNUSED_PAD src0_sel:WORD_1 src1_sel:DWORD
; #define GAS __attribute__((address_space(1)))
; __host__ __device__ __forceinline__ size_t tl_off(int row, int k, int K) { return ((((size_t)(row >> 4) * (size_t)(K >> 5)) + (size_t)(k >> 5)) << 9) + (size_t)((row & 15) * 32 + (k & 31)); }
; __device__ __forceinline__ unsigned pk2(float lo, float hi) { return f2bf(lo) | (f2bf(hi) << 16); }
; __device__ __forceinline__ void p0_prologue(Frame& F) {
;     ...
;                 for (int rh = 0; rh < 2; ++rh) {
;                     const int r0 = 4 * rq + 2 * rh, r1 = r0 + 1;
; #pragma unroll
;                     for (int j = 0; j < 4; ++j) {
;                         const float x0 = v[r0][j].x * rs8[r0] * gg[j].x, x1 = v[r0][j].y * rs8[r0] * gg[j].y, x2 = v[r0][j].z * rs8[r0] * gg[j].z, x3 = v[r0][j].w * rs8[r0] * gg[j].w;
;                         const float y0 = v[r1][j].x * rs8[r1] * gg[j].x, y1 = v[r1][j].y * rs8[r1] * gg[j].y, y2 = v[r1][j].z * rs8[r1] * gg[j].z, y3 = v[r1][j].w * rs8[r1] * gg[j].w;
;                         const unsigned a0 = pk2(x0, x1), a1 = pk2(x2, x3), b0 = pk2(y0, y1), b1 = pk2(y2, y3);
;                         q8[2 * rh][j] = pk4_fp8(x0, x1, x2, x3); q8[2 * rh + 1][j] = pk4_fp8(y0, y1, y2, y3);
;                         const unsigned t0 = lodd ? a0 : b0, t1 = lodd ? a1 : b1;
;                         const unsigned g0 = (unsigned)__builtin_amdgcn_mov_dpp((int)t0, 0xB1, 0xf, 0xf, true), g1 = (unsigned)__builtin_amdgcn_mov_dpp((int)t1, 0xB1, 0xf, 0xf, true);
;                         u32x4 o; o.x = lodd ? g0 : a0; o.y = lodd ? g1 : a1; o.z = lodd ? b0 : g0; o.w = lodd ? b1 : g1;
;                         *(GAS u32x4*)(F.XN + tl_off(m0 + r0 + (lane & 1), 8 * (lane >> 1) + 256 * j, D)) = o;
;                         __builtin_amdgcn_sched_barrier(0);
;                     }
	v_add3_u32 v236, v232, v236, s96
	v_or_b32_sdwa v214, v229, v214 dst_sel:DWORD dst_unused:UNUSED_PAD src0_sel:DWORD src1_sel:WORD_1
	v_and_b32_sdwa v229, v231, v226 dst_sel:DWORD dst_unused:UNUSED_PAD src0_sel:WORD_1 src1_sel:DWORD
	v_add3_u32 v234, v230, v234, s96
	v_add3_u32 v235, v233, v235, s96
	v_and_b32_e32 v230, 0xffff0000, v236
	v_add3_u32 v229, v231, v229, s96
	v_and_b32_e32 v235, 0xffff0000, v235
	v_or_b32_sdwa v230, v230, v234 dst_sel:DWORD dst_unused:UNUSED_PAD src0_sel:DWORD src1_sel:WORD_1
	v_or_b32_sdwa v229, v235, v229 dst_sel:DWORD dst_unused:UNUSED_PAD src0_sel:DWORD src1_sel:WORD_1
	v_cvt_pk_fp8_f32 v238, v231, v233 op_sel:[0,0,1]
	v_cndmask_b32_e64 v231, v216, v230, s[4:5]
	v_cndmask_b32_e64 v232, v214, v229, s[4:5]
	s_nop 0
	v_mov_b32_dpp v234, v231 quad_perm:[1,0,3,2] row_mask:0xf bank_mask:0xf bound_ctrl:1
	v_mov_b32_dpp v231, v232 quad_perm:[1,0,3,2] row_mask:0xf bank_mask:0xf bound_ctrl:1
	v_cndmask_b32_e64 v232, v230, v234, s[4:5]
	v_cndmask_b32_e64 v230, v234, v216, s[4:5]
	v_lshl_add_u64 v[234:235], v[218:219], 0, v[156:157]
	v_cndmask_b32_e64 v233, v229, v231, s[4:5]
	v_cndmask_b32_e64 v231, v231, v214, s[4:5]
	v_lshl_add_u64 v[234:235], v[234:235], 0, v[152:153]
	global_store_dwordx4 v[234:235], v[230:233], off sc1
	s_nop 1
	v_mov_b32_e32 v230, v0
	v_mov_b32_e32 v231, v2
	v_mov_b32_e32 v232, v1
	v_mov_b32_e32 v233, v3
	v_pk_mul_f32 v[230:231], v[230:231], v[204:205] op_sel_hi:[1,0]
	v_pk_mul_f32 v[232:233], v[232:233], v[204:205] op_sel_hi:[1,0]
	v_pk_mul_f32 v[230:231], v[230:231], v[132:133]
	v_pk_mul_f32 v[232:233], v[232:233], v[130:131]
	v_mov_b32_e32 v240, v153
	v_cvt_pk_fp8_f32 v240, v230, v232
	v_mov_b32_e32 v236, v29
	v_mov_b32_e32 v237, v31
	v_mov_b32_e32 v234, v28
	v_mov_b32_e32 v235, v30
	v_pk_mul_f32 v[236:237], v[236:237], v[206:207] op_sel_hi:[1,0]
	v_and_b32_sdwa v214, v233, v226 dst_sel:DWORD dst_unused:UNUSED_PAD src0_sel:WORD_1 src1_sel:DWORD
	v_and_b32_sdwa v216, v232, v226 dst_sel:DWORD dst_unused:UNUSED_PAD src0_sel:WORD_1 src1_sel:DWORD
	v_pk_mul_f32 v[234:235], v[234:235], v[206:207] op_sel_hi:[1,0]
	v_and_b32_sdwa v204, v231, v226 dst_sel:DWORD dst_unused:UNUSED_PAD src0_sel:WORD_1 src1_sel:DWORD
	v_and_b32_sdwa v206, v230, v226 dst_sel:DWORD dst_unused:UNUSED_PAD src0_sel:WORD_1 src1_sel:DWORD
	v_add3_u32 v214, v233, v214, s96
	v_add3_u32 v216, v232, v216, s96
	v_cvt_pk_fp8_f32 v240, v231, v233 op_sel:[0,0,1]
	v_pk_mul_f32 v[232:233], v[236:237], v[130:131]
	v_add3_u32 v206, v230, v206, s96
	v_add3_u32 v204, v231, v204, s96
	v_and_b32_e32 v214, 0xffff0000, v214
	v_and_b32_e32 v216, 0xffff0000, v216
	v_pk_mul_f32 v[230:231], v[234:235], v[132:133]
	v_and_b32_sdwa v229, v233, v226 dst_sel:DWORD dst_unused:UNUSED_PAD src0_sel:WORD_1 src1_sel:DWORD
	v_and_b32_sdwa v234, v232, v226 dst_sel:DWORD dst_unused:UNUSED_PAD src0_sel:WORD_1 src1_sel:DWORD
	v_or_b32_sdwa v204, v214, v204 dst_sel:DWORD dst_unused:UNUSED_PAD src0_sel:DWORD src1_sel:WORD_1
	v_or_b32_sdwa v206, v216, v206 dst_sel:DWORD dst_unused:UNUSED_PAD src0_sel:DWORD src1_sel:WORD_1
	v_and_b32_sdwa v214, v231, v226 dst_sel:DWORD dst_unused:UNUSED_PAD src0_sel:WORD_1 src1_sel:DWORD
	v_and_b32_sdwa v216, v230, v226 dst_sel:DWORD dst_unused:UNUSED_PAD src0_sel:WORD_1 src1_sel:DWORD
	v_add3_u32 v229, v233, v229, s96
	v_add3_u32 v234, v232, v234, s96
	v_mov_b32_e32 v236, v153
	v_add3_u32 v216, v230, v216, s96
	v_add3_u32 v214, v231, v214, s96
	v_and_b32_e32 v229, 0xffff0000, v229
	v_cvt_pk_fp8_f32 v236, v230, v232
	v_and_b32_e32 v230, 0xffff0000, v234
	v_or_b32_sdwa v214, v229, v214 dst_sel:DWORD dst_unused:UNUSED_PAD src0_sel:DWORD src1_sel:WORD_1
	v_or_b32_sdwa v216, v230, v216 dst_sel:DWORD dst_unused:UNUSED_PAD src0_sel:DWORD src1_sel:WORD_1
	v_cndmask_b32_e64 v229, v206, v216, s[4:5]
	v_cndmask_b32_e64 v230, v204, v214, s[4:5]
	v_lshl_add_u64 v[218:219], v[218:219], 0, v[158:159]
	v_mov_b32_dpp v229, v229 quad_perm:[1,0,3,2] row_mask:0xf bank_mask:0xf bound_ctrl:1
	v_mov_b32_dpp v230, v230 quad_perm:[1,0,3,2] row_mask:0xf bank_mask:0xf bound_ctrl:1
	v_cvt_pk_fp8_f32 v236, v231, v233 op_sel:[0,0,1]
	v_cndmask_b32_e64 v233, v214, v230, s[4:5]
	v_cndmask_b32_e64 v232, v216, v229, s[4:5]
	v_cndmask_b32_e64 v231, v230, v204, s[4:5]
	v_cndmask_b32_e64 v230, v229, v206, s[4:5]
	v_lshl_add_u64 v[218:219], v[218:219], 0, v[152:153]
	global_store_dwordx4 v[218:219], v[230:233], off sc1
	v_add_u32_e32 v152, 6, v228
	v_mov_b32_e32 v228, v72
	v_mov_b32_e32 v229, v74
	v_mov_b32_e32 v230, v73
	v_mov_b32_e32 v231, v75
	v_pk_mul_f32 v[228:229], v[228:229], v[200:201] op_sel_hi:[1,0]
	v_pk_mul_f32 v[230:231], v[230:231], v[200:201] op_sel_hi:[1,0]
	v_pk_mul_f32 v[228:229], v[228:229], v[208:209]
	v_pk_mul_f32 v[230:231], v[230:231], v[142:143]
	v_mov_b32_e32 v237, v153
	v_cvt_pk_fp8_f32 v237, v228, v230
	v_mov_b32_e32 v232, v96
	v_mov_b32_e32 v233, v98
	v_mov_b32_e32 v234, v97
	v_mov_b32_e32 v235, v99
	v_pk_mul_f32 v[232:233], v[232:233], v[202:203] op_sel_hi:[1,0]
	v_pk_mul_f32 v[234:235], v[234:235], v[202:203] op_sel_hi:[1,0]
	v_and_b32_sdwa v216, v230, v226 dst_sel:DWORD dst_unused:UNUSED_PAD src0_sel:WORD_1 src1_sel:DWORD
	v_and_b32_sdwa v204, v229, v226 dst_sel:DWORD dst_unused:UNUSED_PAD src0_sel:WORD_1 src1_sel:DWORD
	v_and_b32_sdwa v206, v228, v226 dst_sel:DWORD dst_unused:UNUSED_PAD src0_sel:WORD_1 src1_sel:DWORD
	v_and_b32_sdwa v214, v231, v226 dst_sel:DWORD dst_unused:UNUSED_PAD src0_sel:WORD_1 src1_sel:DWORD
	v_add3_u32 v216, v230, v216, s96
	v_pk_mul_f32 v[208:209], v[232:233], v[208:209]
	v_pk_mul_f32 v[142:143], v[234:235], v[142:143]
	v_mov_b32_e32 v232, v153
	v_add3_u32 v206, v228, v206, s96
	v_add3_u32 v204, v229, v204, s96
; #define GAS __attribute__((address_space(1)))
; __host__ __device__ __forceinline__ size_t tl_off(int row, int k, int K) { return ((((size_t)(row >> 4) * (size_t)(K >> 5)) + (size_t)(k >> 5)) << 9) + (size_t)((row & 15) * 32 + (k & 31)); }
; __device__ __forceinline__ unsigned pk2(float lo, float hi) { return f2bf(lo) | (f2bf(hi) << 16); }
; __device__ __forceinline__ void p0_prologue(Frame& F) {
;     ...
;                 for (int rh = 0; rh < 2; ++rh) {
;                     const int r0 = 4 * rq + 2 * rh, r1 = r0 + 1;
; #pragma unroll
;                     for (int j = 0; j < 4; ++j) {
;                         const float x0 = v[r0][j].x * rs8[r0] * gg[j].x, x1 = v[r0][j].y * rs8[r0] * gg[j].y, x2 = v[r0][j].z * rs8[r0] * gg[j].z, x3 = v[r0][j].w * rs8[r0] * gg[j].w;
;                         const float y0 = v[r1][j].x * rs8[r1] * gg[j].x, y1 = v[r1][j].y * rs8[r1] * gg[j].y, y2 = v[r1][j].z * rs8[r1] * gg[j].z, y3 = v[r1][j].w * rs8[r1] * gg[j].w;
;                         const unsigned a0 = pk2(x0, x1), a1 = pk2(x2, x3), b0 = pk2(y0, y1), b1 = pk2(y2, y3);
;                         q8[2 * rh][j] = pk4_fp8(x0, x1, x2, x3); q8[2 * rh + 1][j] = pk4_fp8(y0, y1, y2, y3);
;                         const unsigned t0 = lodd ? a0 : b0, t1 = lodd ? a1 : b1;
;                         const unsigned g0 = (unsigned)__builtin_amdgcn_mov_dpp((int)t0, 0xB1, 0xf, 0xf, true), g1 = (unsigned)__builtin_amdgcn_mov_dpp((int)t1, 0xB1, 0xf, 0xf, true);
;                         u32x4 o; o.x = lodd ? g0 : a0; o.y = lodd ? g1 : a1; o.z = lodd ? b0 : g0; o.w = lodd ? b1 : g1;
;                         *(GAS u32x4*)(F.XN + tl_off(m0 + r0 + (lane & 1), 8 * (lane >> 1) + 256 * j, D)) = o;
;                         __builtin_amdgcn_sched_barrier(0);
;                     }
	v_add3_u32 v214, v231, v214, s96
	v_and_b32_e32 v216, 0xffff0000, v216
	v_cvt_pk_fp8_f32 v237, v229, v231 op_sel:[0,0,1]
	v_and_b32_sdwa v229, v142, v226 dst_sel:DWORD dst_unused:UNUSED_PAD src0_sel:WORD_1 src1_sel:DWORD
	v_cvt_pk_fp8_f32 v232, v208, v142
	v_and_b32_e32 v214, 0xffff0000, v214
	v_or_b32_sdwa v206, v216, v206 dst_sel:DWORD dst_unused:UNUSED_PAD src0_sel:DWORD src1_sel:WORD_1
	v_and_b32_sdwa v216, v208, v226 dst_sel:DWORD dst_unused:UNUSED_PAD src0_sel:WORD_1 src1_sel:DWORD
	v_and_b32_sdwa v228, v143, v226 dst_sel:DWORD dst_unused:UNUSED_PAD src0_sel:WORD_1 src1_sel:DWORD
	v_add3_u32 v229, v142, v229, s96
	v_or_b32_sdwa v204, v214, v204 dst_sel:DWORD dst_unused:UNUSED_PAD src0_sel:DWORD src1_sel:WORD_1
	v_and_b32_sdwa v214, v209, v226 dst_sel:DWORD dst_unused:UNUSED_PAD src0_sel:WORD_1 src1_sel:DWORD
	v_add3_u32 v216, v208, v216, s96
	v_add3_u32 v228, v143, v228, s96
	v_and_b32_e32 v142, 0xffff0000, v229
	v_ashrrev_i32_e32 v218, 4, v152
	v_add3_u32 v214, v209, v214, s96
	v_and_b32_e32 v228, 0xffff0000, v228
	v_or_b32_sdwa v142, v142, v216 dst_sel:DWORD dst_unused:UNUSED_PAD src0_sel:DWORD src1_sel:WORD_1
	v_ashrrev_i32_e32 v219, 31, v218
	v_or_b32_sdwa v208, v228, v214 dst_sel:DWORD dst_unused:UNUSED_PAD src0_sel:DWORD src1_sel:WORD_1
	v_cvt_pk_fp8_f32 v232, v209, v143 op_sel:[0,0,1]
	v_cndmask_b32_e64 v143, v206, v142, s[4:5]
	v_lshlrev_b32_e32 v152, 5, v152
	v_lshlrev_b64 v[218:219], 15, v[218:219]
	v_cndmask_b32_e64 v209, v204, v208, s[4:5]
	v_mov_b32_dpp v143, v143 quad_perm:[1,0,3,2] row_mask:0xf bank_mask:0xf bound_ctrl:1
	v_and_or_b32 v152, v152, s54, v220
	v_mov_b32_dpp v209, v209 quad_perm:[1,0,3,2] row_mask:0xf bank_mask:0xf bound_ctrl:1
	v_cndmask_b32_e64 v230, v142, v143, s[4:5]
	v_cndmask_b32_e64 v228, v143, v206, s[4:5]
	v_lshl_add_u64 v[142:143], s[62:63], 0, v[218:219]
	v_cndmask_b32_e64 v231, v208, v209, s[4:5]
	v_cndmask_b32_e64 v229, v209, v204, s[4:5]
	v_lshl_add_u64 v[208:209], v[142:143], 0, v[148:149]
	v_lshlrev_b32_e32 v152, 1, v152
	v_lshl_add_u64 v[208:209], v[208:209], 0, v[152:153]
	global_store_dwordx4 v[208:209], v[228:231], off sc1
	v_mov_b32_e32 v208, v56
	v_mov_b32_e32 v209, v58
	v_mov_b32_e32 v218, v57
	v_mov_b32_e32 v219, v59
	v_pk_mul_f32 v[208:209], v[208:209], v[200:201] op_sel_hi:[1,0]
	v_pk_mul_f32 v[218:219], v[218:219], v[200:201] op_sel_hi:[1,0]
	v_pk_mul_f32 v[208:209], v[208:209], v[140:141]
	v_pk_mul_f32 v[218:219], v[218:219], v[138:139]
	v_mov_b32_e32 v233, v153
	v_mov_b32_e32 v228, v88
	v_mov_b32_e32 v229, v90
	v_mov_b32_e32 v230, v89
	v_mov_b32_e32 v231, v91
	v_and_b32_sdwa v214, v219, v226 dst_sel:DWORD dst_unused:UNUSED_PAD src0_sel:WORD_1 src1_sel:DWORD
	v_cvt_pk_fp8_f32 v233, v208, v218
	v_pk_mul_f32 v[228:229], v[228:229], v[202:203] op_sel_hi:[1,0]
	v_pk_mul_f32 v[230:231], v[230:231], v[202:203] op_sel_hi:[1,0]
	v_and_b32_sdwa v204, v209, v226 dst_sel:DWORD dst_unused:UNUSED_PAD src0_sel:WORD_1 src1_sel:DWORD
	v_and_b32_sdwa v216, v218, v226 dst_sel:DWORD dst_unused:UNUSED_PAD src0_sel:WORD_1 src1_sel:DWORD
	v_add3_u32 v214, v219, v214, s96
	v_and_b32_sdwa v206, v208, v226 dst_sel:DWORD dst_unused:UNUSED_PAD src0_sel:WORD_1 src1_sel:DWORD
	v_add3_u32 v204, v209, v204, s96
	v_add3_u32 v216, v218, v216, s96
	v_and_b32_e32 v214, 0xffff0000, v214
	v_pk_mul_f32 v[140:141], v[228:229], v[140:141]
	v_pk_mul_f32 v[138:139], v[230:231], v[138:139]
	v_mov_b32_e32 v228, v153
	v_add3_u32 v206, v208, v206, s96
	v_and_b32_e32 v208, 0xffff0000, v216
	v_or_b32_sdwa v204, v214, v204 dst_sel:DWORD dst_unused:UNUSED_PAD src0_sel:DWORD src1_sel:WORD_1
	v_and_b32_sdwa v214, v139, v226 dst_sel:DWORD dst_unused:UNUSED_PAD src0_sel:WORD_1 src1_sel:DWORD
	v_and_b32_sdwa v216, v138, v226 dst_sel:DWORD dst_unused:UNUSED_PAD src0_sel:WORD_1 src1_sel:DWORD
	v_cvt_pk_fp8_f32 v228, v140, v138
	v_or_b32_sdwa v206, v208, v206 dst_sel:DWORD dst_unused:UNUSED_PAD src0_sel:DWORD src1_sel:WORD_1
	v_cvt_pk_fp8_f32 v233, v209, v219 op_sel:[0,0,1]
	v_and_b32_sdwa v208, v141, v226 dst_sel:DWORD dst_unused:UNUSED_PAD src0_sel:WORD_1 src1_sel:DWORD
	v_and_b32_sdwa v209, v140, v226 dst_sel:DWORD dst_unused:UNUSED_PAD src0_sel:WORD_1 src1_sel:DWORD
	v_add3_u32 v214, v139, v214, s96
	v_add3_u32 v216, v138, v216, s96
	v_add3_u32 v209, v140, v209, s96
	v_add3_u32 v208, v141, v208, s96
	v_and_b32_e32 v214, 0xffff0000, v214
	v_and_b32_e32 v138, 0xffff0000, v216
	v_or_b32_sdwa v140, v214, v208 dst_sel:DWORD dst_unused:UNUSED_PAD src0_sel:DWORD src1_sel:WORD_1
	v_or_b32_sdwa v138, v138, v209 dst_sel:DWORD dst_unused:UNUSED_PAD src0_sel:DWORD src1_sel:WORD_1
	v_cvt_pk_fp8_f32 v228, v141, v139 op_sel:[0,0,1]
	v_cndmask_b32_e64 v139, v206, v138, s[4:5]
	v_cndmask_b32_e64 v141, v204, v140, s[4:5]
	s_nop 0
	v_mov_b32_dpp v208, v139 quad_perm:[1,0,3,2] row_mask:0xf bank_mask:0xf bound_ctrl:1
	v_mov_b32_dpp v139, v141 quad_perm:[1,0,3,2] row_mask:0xf bank_mask:0xf bound_ctrl:1
	v_cndmask_b32_e64 v141, v140, v139, s[4:5]
	v_cndmask_b32_e64 v140, v138, v208, s[4:5]
	v_cndmask_b32_e64 v138, v208, v206, s[4:5]
	v_lshl_add_u64 v[208:209], v[142:143], 0, v[154:155]
	v_cndmask_b32_e64 v139, v139, v204, s[4:5]
	v_lshl_add_u64 v[208:209], v[208:209], 0, v[152:153]
	global_store_dwordx4 v[208:209], v[138:141], off sc1
	s_nop 1
	v_mov_b32_e32 v138, v52
	v_mov_b32_e32 v139, v54
	v_mov_b32_e32 v140, v53
	v_mov_b32_e32 v141, v55
	v_pk_mul_f32 v[138:139], v[138:139], v[200:201] op_sel_hi:[1,0]
	v_pk_mul_f32 v[140:141], v[140:141], v[200:201] op_sel_hi:[1,0]
	v_pk_mul_f32 v[138:139], v[138:139], v[136:137]
	v_pk_mul_f32 v[140:141], v[140:141], v[134:135]
	v_mov_b32_e32 v229, v153
	v_mov_b32_e32 v208, v84
	v_mov_b32_e32 v209, v86
; #define GAS __attribute__((address_space(1)))
; __host__ __device__ __forceinline__ size_t tl_off(int row, int k, int K) { return ((((size_t)(row >> 4) * (size_t)(K >> 5)) + (size_t)(k >> 5)) << 9) + (size_t)((row & 15) * 32 + (k & 31)); }
; __device__ __forceinline__ unsigned pk2(float lo, float hi) { return f2bf(lo) | (f2bf(hi) << 16); }
; __device__ __forceinline__ void p0_prologue(Frame& F) {
;     ...
;                 for (int rh = 0; rh < 2; ++rh) {
;                     const int r0 = 4 * rq + 2 * rh, r1 = r0 + 1;
; #pragma unroll
;                     for (int j = 0; j < 4; ++j) {
;                         const float x0 = v[r0][j].x * rs8[r0] * gg[j].x, x1 = v[r0][j].y * rs8[r0] * gg[j].y, x2 = v[r0][j].z * rs8[r0] * gg[j].z, x3 = v[r0][j].w * rs8[r0] * gg[j].w;
;                         const float y0 = v[r1][j].x * rs8[r1] * gg[j].x, y1 = v[r1][j].y * rs8[r1] * gg[j].y, y2 = v[r1][j].z * rs8[r1] * gg[j].z, y3 = v[r1][j].w * rs8[r1] * gg[j].w;
;                         const unsigned a0 = pk2(x0, x1), a1 = pk2(x2, x3), b0 = pk2(y0, y1), b1 = pk2(y2, y3);
;                         q8[2 * rh][j] = pk4_fp8(x0, x1, x2, x3); q8[2 * rh + 1][j] = pk4_fp8(y0, y1, y2, y3);
;                         const unsigned t0 = lodd ? a0 : b0, t1 = lodd ? a1 : b1;
;                         const unsigned g0 = (unsigned)__builtin_amdgcn_mov_dpp((int)t0, 0xB1, 0xf, 0xf, true), g1 = (unsigned)__builtin_amdgcn_mov_dpp((int)t1, 0xB1, 0xf, 0xf, true);
;                         u32x4 o; o.x = lodd ? g0 : a0; o.y = lodd ? g1 : a1; o.z = lodd ? b0 : g0; o.w = lodd ? b1 : g1;
;                         *(GAS u32x4*)(F.XN + tl_off(m0 + r0 + (lane & 1), 8 * (lane >> 1) + 256 * j, D)) = o;
;                         __builtin_amdgcn_sched_barrier(0);
;                     }
	v_mov_b32_e32 v218, v85
	v_mov_b32_e32 v219, v87
	v_and_b32_sdwa v214, v141, v226 dst_sel:DWORD dst_unused:UNUSED_PAD src0_sel:WORD_1 src1_sel:DWORD
	v_and_b32_sdwa v216, v140, v226 dst_sel:DWORD dst_unused:UNUSED_PAD src0_sel:WORD_1 src1_sel:DWORD
	v_cvt_pk_fp8_f32 v229, v138, v140
	v_pk_mul_f32 v[208:209], v[208:209], v[202:203] op_sel_hi:[1,0]
	v_pk_mul_f32 v[218:219], v[218:219], v[202:203] op_sel_hi:[1,0]
	v_and_b32_sdwa v204, v139, v226 dst_sel:DWORD dst_unused:UNUSED_PAD src0_sel:WORD_1 src1_sel:DWORD
	v_and_b32_sdwa v206, v138, v226 dst_sel:DWORD dst_unused:UNUSED_PAD src0_sel:WORD_1 src1_sel:DWORD
	v_add3_u32 v214, v141, v214, s96
	v_add3_u32 v216, v140, v216, s96
	v_add3_u32 v206, v138, v206, s96
	v_add3_u32 v204, v139, v204, s96
	v_and_b32_e32 v214, 0xffff0000, v214
	v_and_b32_e32 v138, 0xffff0000, v216
	v_pk_mul_f32 v[136:137], v[208:209], v[136:137]
	v_pk_mul_f32 v[134:135], v[218:219], v[134:135]
	v_mov_b32_e32 v208, v153
	v_or_b32_sdwa v140, v214, v204 dst_sel:DWORD dst_unused:UNUSED_PAD src0_sel:DWORD src1_sel:WORD_1
	v_or_b32_sdwa v138, v138, v206 dst_sel:DWORD dst_unused:UNUSED_PAD src0_sel:DWORD src1_sel:WORD_1
	v_and_b32_sdwa v204, v135, v226 dst_sel:DWORD dst_unused:UNUSED_PAD src0_sel:WORD_1 src1_sel:DWORD
	v_and_b32_sdwa v206, v134, v226 dst_sel:DWORD dst_unused:UNUSED_PAD src0_sel:WORD_1 src1_sel:DWORD
	v_cvt_pk_fp8_f32 v208, v136, v134
	v_cvt_pk_fp8_f32 v229, v139, v141 op_sel:[0,0,1]
	v_and_b32_sdwa v139, v137, v226 dst_sel:DWORD dst_unused:UNUSED_PAD src0_sel:WORD_1 src1_sel:DWORD
	v_and_b32_sdwa v141, v136, v226 dst_sel:DWORD dst_unused:UNUSED_PAD src0_sel:WORD_1 src1_sel:DWORD
	v_add3_u32 v204, v135, v204, s96
	v_add3_u32 v206, v134, v206, s96
	v_add3_u32 v141, v136, v141, s96
	v_add3_u32 v139, v137, v139, s96
	v_and_b32_e32 v204, 0xffff0000, v204
	v_and_b32_e32 v134, 0xffff0000, v206
	v_or_b32_sdwa v136, v204, v139 dst_sel:DWORD dst_unused:UNUSED_PAD src0_sel:DWORD src1_sel:WORD_1
	v_or_b32_sdwa v134, v134, v141 dst_sel:DWORD dst_unused:UNUSED_PAD src0_sel:DWORD src1_sel:WORD_1
	v_cvt_pk_fp8_f32 v208, v137, v135 op_sel:[0,0,1]
	v_cndmask_b32_e64 v135, v138, v134, s[4:5]
	v_cndmask_b32_e64 v137, v140, v136, s[4:5]
	s_nop 0
	v_mov_b32_dpp v139, v135 quad_perm:[1,0,3,2] row_mask:0xf bank_mask:0xf bound_ctrl:1
	v_mov_b32_dpp v135, v137 quad_perm:[1,0,3,2] row_mask:0xf bank_mask:0xf bound_ctrl:1
	v_cndmask_b32_e64 v137, v136, v135, s[4:5]
	v_cndmask_b32_e64 v136, v134, v139, s[4:5]
	v_cndmask_b32_e64 v134, v139, v138, s[4:5]
	v_lshl_add_u64 v[138:139], v[142:143], 0, v[156:157]
	v_cndmask_b32_e64 v135, v135, v140, s[4:5]
	v_lshl_add_u64 v[138:139], v[138:139], 0, v[152:153]
	global_store_dwordx4 v[138:139], v[134:137], off sc1
	s_nop 1
	v_mov_b32_e32 v134, v60
	v_mov_b32_e32 v135, v62
	v_mov_b32_e32 v136, v61
	v_mov_b32_e32 v137, v63
	v_pk_mul_f32 v[134:135], v[134:135], v[200:201] op_sel_hi:[1,0]
	v_pk_mul_f32 v[136:137], v[136:137], v[200:201] op_sel_hi:[1,0]
	v_pk_mul_f32 v[134:135], v[134:135], v[132:133]
	v_pk_mul_f32 v[136:137], v[136:137], v[130:131]
	v_mov_b32_e32 v209, v153
	v_mov_b32_e32 v138, v92
	v_mov_b32_e32 v139, v94
	v_mov_b32_e32 v140, v93
	v_mov_b32_e32 v141, v95
	v_cvt_pk_fp8_f32 v209, v134, v136
	v_pk_mul_f32 v[138:139], v[138:139], v[202:203] op_sel_hi:[1,0]
	v_pk_mul_f32 v[140:141], v[140:141], v[202:203] op_sel_hi:[1,0]
	v_pk_mul_f32 v[132:133], v[138:139], v[132:133]
	v_pk_mul_f32 v[130:131], v[140:141], v[130:131]
	v_mov_b32_e32 v140, v153
	v_and_b32_sdwa v200, v135, v226 dst_sel:DWORD dst_unused:UNUSED_PAD src0_sel:WORD_1 src1_sel:DWORD
	v_and_b32_sdwa v204, v137, v226 dst_sel:DWORD dst_unused:UNUSED_PAD src0_sel:WORD_1 src1_sel:DWORD
	v_and_b32_sdwa v206, v136, v226 dst_sel:DWORD dst_unused:UNUSED_PAD src0_sel:WORD_1 src1_sel:DWORD
	v_and_b32_sdwa v138, v131, v226 dst_sel:DWORD dst_unused:UNUSED_PAD src0_sel:WORD_1 src1_sel:DWORD
	v_and_b32_sdwa v139, v130, v226 dst_sel:DWORD dst_unused:UNUSED_PAD src0_sel:WORD_1 src1_sel:DWORD
	v_cvt_pk_fp8_f32 v140, v132, v130
	v_and_b32_sdwa v202, v134, v226 dst_sel:DWORD dst_unused:UNUSED_PAD src0_sel:WORD_1 src1_sel:DWORD
	v_add3_u32 v200, v135, v200, s96
	v_add3_u32 v204, v137, v204, s96
	v_add3_u32 v206, v136, v206, s96
	v_cvt_pk_fp8_f32 v209, v135, v137 op_sel:[0,0,1]
	v_and_b32_sdwa v135, v133, v226 dst_sel:DWORD dst_unused:UNUSED_PAD src0_sel:WORD_1 src1_sel:DWORD
	v_and_b32_sdwa v137, v132, v226 dst_sel:DWORD dst_unused:UNUSED_PAD src0_sel:WORD_1 src1_sel:DWORD
	v_add3_u32 v138, v131, v138, s96
	v_add3_u32 v139, v130, v139, s96
	v_add3_u32 v202, v134, v202, s96
	v_and_b32_e32 v204, 0xffff0000, v204
	v_and_b32_e32 v134, 0xffff0000, v206
	v_add3_u32 v137, v132, v137, s96
	v_add3_u32 v135, v133, v135, s96
	v_and_b32_e32 v138, 0xffff0000, v138
	v_and_b32_e32 v130, 0xffff0000, v139
	v_or_b32_sdwa v136, v204, v200 dst_sel:DWORD dst_unused:UNUSED_PAD src0_sel:DWORD src1_sel:WORD_1
	v_or_b32_sdwa v134, v134, v202 dst_sel:DWORD dst_unused:UNUSED_PAD src0_sel:DWORD src1_sel:WORD_1
	v_or_b32_sdwa v132, v138, v135 dst_sel:DWORD dst_unused:UNUSED_PAD src0_sel:DWORD src1_sel:WORD_1
	v_or_b32_sdwa v130, v130, v137 dst_sel:DWORD dst_unused:UNUSED_PAD src0_sel:DWORD src1_sel:WORD_1
; #define GAS __attribute__((address_space(1)))
; __device__ __forceinline__ size_t tl8_off(int row, int k, int K) { return (size_t)tl_off(row, k >> 1, K >> 1) * 2 + (k & 1); }
; __device__ __forceinline__ void p0_prologue(Frame& F) {
;     ...
;                 for (int j = 0; j < 4; ++j) {
;                     const unsigned t0 = q8[0][j], t1 = q8[1][j], t2 = q8[2][j], t3 = q8[3][j];
;                     const unsigned sA = lodd ? t0 : t1, sB = lodd ? t2 : t3;
;                     const unsigned rA = (unsigned)__builtin_amdgcn_mov_dpp((int)sA, 0xB1, 0xf, 0xf, true), rB = (unsigned)__builtin_amdgcn_mov_dpp((int)sB, 0xB1, 0xf, 0xf, true);
;                     const unsigned u0 = lodd ? rA : t0, u1 = lodd ? t1 : rA;
;                     const unsigned w0 = lodd ? rB : t2, w1 = lodd ? t3 : rB;
;                     const unsigned c0 = lhi ? u0 : w0, c1 = lhi ? u1 : w1;
;                     const unsigned d0 = (unsigned)__builtin_amdgcn_mov_dpp((int)c0, 0x4E, 0xf, 0xf, true), d1 = (unsigned)__builtin_amdgcn_mov_dpp((int)c1, 0x4E, 0xf, 0xf, true);
;                     u32x4 o; o.x = lhi ? d0 : u0; o.y = lhi ? d1 : u1; o.z = lhi ? w0 : d0; o.w = lhi ? w1 : d1;
;                     *(GAS u32x4*)(F.XN8 + tl8_off(m0 + 4 * rq + (lane & 3), 16 * (lane >> 2) + 256 * j, D)) = o;
;                     __builtin_amdgcn_sched_barrier(0);
	v_cvt_pk_fp8_f32 v140, v133, v131 op_sel:[0,0,1]
	v_cndmask_b32_e64 v131, v134, v130, s[4:5]
	v_cndmask_b32_e64 v133, v136, v132, s[4:5]
	s_nop 0
	v_mov_b32_dpp v135, v131 quad_perm:[1,0,3,2] row_mask:0xf bank_mask:0xf bound_ctrl:1
	v_mov_b32_dpp v131, v133 quad_perm:[1,0,3,2] row_mask:0xf bank_mask:0xf bound_ctrl:1
	v_cndmask_b32_e64 v133, v132, v131, s[4:5]
	v_cndmask_b32_e64 v132, v130, v135, s[4:5]
	v_cndmask_b32_e64 v130, v135, v134, s[4:5]
	v_lshl_add_u64 v[134:135], v[142:143], 0, v[158:159]
	v_cndmask_b32_e64 v131, v131, v136, s[4:5]
	v_lshl_add_u64 v[134:135], v[134:135], 0, v[152:153]
	global_store_dwordx4 v[134:135], v[130:133], off sc1
	s_nop 1
	v_add_u32_e32 v132, 4, v227
	v_ashrrev_i32_e32 v130, 4, v132
	v_ashrrev_i32_e32 v131, 31, v130
	v_lshlrev_b32_e32 v132, 6, v132
	v_and_or_b32 v152, v132, s95, v222
	v_lshlrev_b64 v[132:133], 14, v[130:131]
	v_cndmask_b32_e64 v130, v128, v129, s[4:5]
	v_cndmask_b32_e64 v131, v237, v232, s[4:5]
	v_lshl_add_u64 v[132:133], s[64:65], 0, v[132:133]
	v_mov_b32_dpp v130, v130 quad_perm:[1,0,3,2] row_mask:0xf bank_mask:0xf bound_ctrl:1
	v_mov_b32_dpp v131, v131 quad_perm:[1,0,3,2] row_mask:0xf bank_mask:0xf bound_ctrl:1
	v_cndmask_b32_e64 v128, v130, v128, s[4:5]
	v_cndmask_b32_e64 v129, v129, v130, s[4:5]
	v_cndmask_b32_e64 v130, v131, v237, s[4:5]
	v_cndmask_b32_e64 v131, v232, v131, s[4:5]
	v_cndmask_b32_e64 v134, v128, v130, s[6:7]
	v_cndmask_b32_e64 v135, v129, v131, s[6:7]
	s_nop 0
	v_mov_b32_dpp v134, v134 quad_perm:[2,3,0,1] row_mask:0xf bank_mask:0xf bound_ctrl:1
	v_mov_b32_dpp v135, v135 quad_perm:[2,3,0,1] row_mask:0xf bank_mask:0xf bound_ctrl:1
	v_cndmask_b32_e64 v128, v134, v128, s[6:7]
	v_cndmask_b32_e64 v129, v135, v129, s[6:7]
	v_cndmask_b32_e64 v130, v130, v134, s[6:7]
	v_cndmask_b32_e64 v131, v131, v135, s[6:7]
	v_lshl_add_u64 v[134:135], v[132:133], 0, v[150:151]
	v_lshl_add_u64 v[134:135], v[134:135], 0, v[152:153]
	global_store_dwordx4 v[134:135], v[128:131], off sc1
	s_nop 1
	v_cndmask_b32_e64 v128, v210, v212, s[4:5]
	v_cndmask_b32_e64 v129, v233, v228, s[4:5]
	s_nop 0
	v_mov_b32_dpp v128, v128 quad_perm:[1,0,3,2] row_mask:0xf bank_mask:0xf bound_ctrl:1
	v_mov_b32_dpp v129, v129 quad_perm:[1,0,3,2] row_mask:0xf bank_mask:0xf bound_ctrl:1
	v_cndmask_b32_e64 v130, v128, v210, s[4:5]
	v_cndmask_b32_e64 v131, v212, v128, s[4:5]
	v_cndmask_b32_e64 v134, v129, v233, s[4:5]
	v_cndmask_b32_e64 v135, v228, v129, s[4:5]
	v_cndmask_b32_e64 v128, v130, v134, s[6:7]
	v_cndmask_b32_e64 v129, v131, v135, s[6:7]
	s_nop 0
	v_mov_b32_dpp v136, v128 quad_perm:[2,3,0,1] row_mask:0xf bank_mask:0xf bound_ctrl:1
	v_mov_b32_dpp v137, v129 quad_perm:[2,3,0,1] row_mask:0xf bank_mask:0xf bound_ctrl:1
	v_cndmask_b32_e64 v128, v136, v130, s[6:7]
	v_cndmask_b32_e64 v129, v137, v131, s[6:7]
	v_cndmask_b32_e64 v130, v134, v136, s[6:7]
	v_cndmask_b32_e64 v131, v135, v137, s[6:7]
	v_lshl_add_u64 v[134:135], v[132:133], 0, v[160:161]
	v_lshl_add_u64 v[134:135], v[134:135], 0, v[152:153]
	global_store_dwordx4 v[134:135], v[128:131], off sc1
	s_nop 1
	v_cndmask_b32_e64 v128, v239, v238, s[4:5]
	v_cndmask_b32_e64 v129, v229, v208, s[4:5]
	s_nop 0
	v_mov_b32_dpp v128, v128 quad_perm:[1,0,3,2] row_mask:0xf bank_mask:0xf bound_ctrl:1
	v_mov_b32_dpp v129, v129 quad_perm:[1,0,3,2] row_mask:0xf bank_mask:0xf bound_ctrl:1
	v_cndmask_b32_e64 v130, v128, v239, s[4:5]
	v_cndmask_b32_e64 v131, v238, v128, s[4:5]
	v_cndmask_b32_e64 v134, v129, v229, s[4:5]
	v_cndmask_b32_e64 v135, v208, v129, s[4:5]
	v_cndmask_b32_e64 v128, v130, v134, s[6:7]
	v_cndmask_b32_e64 v129, v131, v135, s[6:7]
	s_nop 0
	v_mov_b32_dpp v136, v128 quad_perm:[2,3,0,1] row_mask:0xf bank_mask:0xf bound_ctrl:1
	v_mov_b32_dpp v137, v129 quad_perm:[2,3,0,1] row_mask:0xf bank_mask:0xf bound_ctrl:1
	v_cndmask_b32_e64 v128, v136, v130, s[6:7]
	v_cndmask_b32_e64 v129, v137, v131, s[6:7]
	v_cndmask_b32_e64 v130, v134, v136, s[6:7]
	v_cndmask_b32_e64 v131, v135, v137, s[6:7]
	v_lshl_add_u64 v[134:135], v[132:133], 0, v[162:163]
	v_lshl_add_u64 v[134:135], v[134:135], 0, v[152:153]
	global_store_dwordx4 v[134:135], v[128:131], off sc1
	s_nop 1
	v_cndmask_b32_e64 v128, v240, v236, s[4:5]
	v_cndmask_b32_e64 v129, v209, v140, s[4:5]
	v_lshl_add_u64 v[132:133], v[132:133], 0, v[164:165]
	v_mov_b32_dpp v128, v128 quad_perm:[1,0,3,2] row_mask:0xf bank_mask:0xf bound_ctrl:1
	v_mov_b32_dpp v129, v129 quad_perm:[1,0,3,2] row_mask:0xf bank_mask:0xf bound_ctrl:1
	v_cndmask_b32_e64 v130, v128, v240, s[4:5]
	v_cndmask_b32_e64 v131, v236, v128, s[4:5]
	v_cndmask_b32_e64 v134, v129, v209, s[4:5]
	v_cndmask_b32_e64 v135, v140, v129, s[4:5]
	v_cndmask_b32_e64 v128, v130, v134, s[6:7]
	v_cndmask_b32_e64 v129, v131, v135, s[6:7]
	v_lshl_add_u64 v[132:133], v[132:133], 0, v[152:153]
	v_mov_b32_dpp v136, v128 quad_perm:[2,3,0,1] row_mask:0xf bank_mask:0xf bound_ctrl:1
	v_mov_b32_dpp v137, v129 quad_perm:[2,3,0,1] row_mask:0xf bank_mask:0xf bound_ctrl:1
	v_cndmask_b32_e64 v128, v136, v130, s[6:7]
	v_cndmask_b32_e64 v129, v137, v131, s[6:7]
	v_cndmask_b32_e64 v130, v134, v136, s[6:7]
	v_cndmask_b32_e64 v131, v135, v137, s[6:7]
	global_store_dwordx4 v[132:133], v[128:131], off sc1
